# K-loops: brief priority windows kept only in the MFMA blocks whose partner load segment has 16 LDS reads (SP1), removed from the SP2 blocks
# speedup vs baseline: 1.0013x; 1.0013x over previous
; #define PG8_STAGE(bufoff, gbase, voff) do { _Pragma("unroll") for (int _i = 0; _i < 2; ++_i) \
;         __builtin_amdgcn_global_load_lds((const unsigned*)((const char*)(gbase) + (voff)[_i]), (PG8_LAS unsigned*)(lds + (bufoff) + ldsw + _i * 8192), 16, 0, 0); } while (0)
; #define PG8_LDA(dst, b, h) do { _Pragma("unroll") for (int m = 0; m < 4; ++m) _Pragma("unroll") for (int k = 0; k < 2; ++k) dst[m][k] = *(const PG8_LAS bf16x8*)(lds + PG8_SA(b, h) + aoff + m * 2048 + k * 1024); } while (0)
; #define PG8_LDB(dst, b, h) do { _Pragma("unroll") for (int n = 0; n < 2; ++n) _Pragma("unroll") for (int k = 0; k < 2; ++k) dst[n][k] = *(const PG8_LAS bf16x8*)(lds + PG8_SB(b, h) + boff + n * 2048 + k * 1024); } while (0)
; #define PG8_MMA(ai, bj, At, Bt) do { __builtin_amdgcn_s_setprio(1); _Pragma("unroll") for (int m = 0; m < 4; ++m) _Pragma("unroll") for (int n = 0; n < 2; ++n) _Pragma("unroll") for (int k = 0; k < 2; ++k) \
;         acc[ai][bj][m][n] = __builtin_amdgcn_mfma_f32_16x16x32_bf16(Bt[n][k], At[m][k], acc[ai][bj][m][n], 0, 0, 0); __builtin_amdgcn_s_setprio(0); } while (0)
; #define PG8_WAIT_V(n) asm volatile("s_waitcnt vmcnt(" #n ")" ::: "memory")
; #define PG8_WAIT_L(n) asm volatile("s_waitcnt lgkmcnt(" #n ")" ::: "memory")
; template <class Epi, class Sched, bool ALIGN_EPI = false, bool SP2 = false>
; __device__ __forceinline__ void gemm_phase(PG8_LAS unsigned char* lds, const Gemm g, const Sched& S, const Epi& E) {
;     ...
;             const bool last = (t == nt - 2);
;             const char* a1 = cA + (size_t)(t + 1) * kstep;
;             const char* a2 = last ? nA : cA + (size_t)(t + 2) * kstep; const char* b2 = last ? nB : cB + (size_t)(t + 2) * kstep;
;             const char* a3 = a2 + kstep; const char* b3 = b2 + kstep;
;             if (last && has_next) S.a_ready(nxt);
;             if constexpr (SP2) {
;             PG8_LDB(B0, 0, 0); PG8_LDB(B1, 0, 1); PG8_SCHED; PG8_LDA(At, 0, 0); PG8_STAGE(PG8_SA(1, 1), a1 + hstep, voffA);
;             PG8_WAIT_V(8); PG8_WAIT_L(0); PG8_BAR; PG8_MMA(0, 0, At, B0); PG8_MMA(0, 1, At, B1); PG8_BAR; PG8_SCHED;
;             PG8_LDA(At, 0, 1); PG8_STAGE(PG8_SB(0, 0), b2, voffB); PG8_STAGE(PG8_SB(0, 1), b2 + hstep, voffB); PG8_STAGE(PG8_SA(0, 0), a2, voffA);
;             PG8_WAIT_V(8); PG8_WAIT_L(0); PG8_BAR; PG8_MMA(1, 0, At, B0); PG8_MMA(1, 1, At, B1); PG8_BAR; PG8_SCHED;
.LBB0_36:
	s_add_u32 s18, s58, 0xffe00080
	s_addc_u32 s19, s59, -1
	s_add_i32 s47, 0, 0x10000
	s_cmpk_eq_i32 s46, 0x7c
	s_cselect_b32 s63, s45, s19
	s_cselect_b32 s62, s73, s18
	v_add_u32_e32 v160, s47, v143
	s_cselect_b32 s19, s37, s79
	s_cselect_b32 s18, s84, s78
	s_add_i32 s80, 0, 0x14000
	ds_read_b128 v[156:159], v160
	ds_read_b128 v[164:167], v160 offset:1024
	ds_read_b128 v[168:171], v160 offset:2048
	ds_read_b128 v[172:175], v160 offset:3072
	v_add_u32_e32 v160, s80, v143
	ds_read_b128 v[176:179], v160
	ds_read_b128 v[180:183], v160 offset:1024
	ds_read_b128 v[184:187], v160 offset:2048
	ds_read_b128 v[204:207], v160 offset:3072
	v_lshl_add_u64 v[160:161], s[58:59], 0, v[152:153]
	s_add_i32 m0, s5, 0xc000
	ds_read_b128 v[208:211], v163
	ds_read_b128 v[212:215], v163 offset:1024
	ds_read_b128 v[216:219], v163 offset:2048
	ds_read_b128 v[220:223], v163 offset:3072
	ds_read_b128 v[224:227], v163 offset:4096
	ds_read_b128 v[228:231], v163 offset:5120
	ds_read_b128 v[232:235], v163 offset:6144
	ds_read_b128 v[236:239], v163 offset:7168
	global_load_lds_dwordx4 v[160:161], off
	v_lshl_add_u64 v[160:161], s[58:59], 0, v[154:155]
	s_add_i32 m0, s5, 0xe000
	s_nop 0
	global_load_lds_dwordx4 v[160:161], off
	s_nop 0
	s_waitcnt vmcnt(8)
	s_waitcnt lgkmcnt(0)
	s_setprio 1
	s_barrier
	v_mfma_f32_16x16x32_bf16 v[126:129], v[156:159], v[208:211], v[126:129]
	v_mfma_f32_16x16x32_bf16 v[122:125], v[168:171], v[208:211], v[122:125]
	v_mfma_f32_16x16x32_bf16 v[110:113], v[156:159], v[216:219], v[110:113]
	v_mfma_f32_16x16x32_bf16 v[106:109], v[168:171], v[216:219], v[106:109]
	v_mfma_f32_16x16x32_bf16 v[94:97], v[156:159], v[224:227], v[94:97]
	v_mfma_f32_16x16x32_bf16 v[90:93], v[168:171], v[224:227], v[90:93]
	v_mfma_f32_16x16x32_bf16 v[78:81], v[156:159], v[232:235], v[78:81]
	v_mfma_f32_16x16x32_bf16 v[74:77], v[168:171], v[232:235], v[74:77]
	s_setprio 0
	s_setprio 1
	v_mfma_f32_16x16x32_bf16 v[126:129], v[164:167], v[212:215], v[126:129]
	v_mfma_f32_16x16x32_bf16 v[122:125], v[172:175], v[212:215], v[122:125]
	v_mfma_f32_16x16x32_bf16 v[110:113], v[164:167], v[220:223], v[110:113]
	v_mfma_f32_16x16x32_bf16 v[106:109], v[172:175], v[220:223], v[106:109]
	v_mfma_f32_16x16x32_bf16 v[94:97], v[164:167], v[228:231], v[94:97]
	v_mfma_f32_16x16x32_bf16 v[90:93], v[172:175], v[228:231], v[90:93]
	v_mfma_f32_16x16x32_bf16 v[78:81], v[164:167], v[236:239], v[78:81]
	v_mfma_f32_16x16x32_bf16 v[74:77], v[172:175], v[236:239], v[74:77]
	s_setprio 0
	s_setprio 1
	v_mfma_f32_16x16x32_bf16 v[118:121], v[176:179], v[208:211], v[118:121]
	v_mfma_f32_16x16x32_bf16 v[114:117], v[184:187], v[208:211], v[114:117]
	v_mfma_f32_16x16x32_bf16 v[102:105], v[176:179], v[216:219], v[102:105]
	v_mfma_f32_16x16x32_bf16 v[98:101], v[184:187], v[216:219], v[98:101]
	v_mfma_f32_16x16x32_bf16 v[86:89], v[176:179], v[224:227], v[86:89]
	v_mfma_f32_16x16x32_bf16 v[82:85], v[184:187], v[224:227], v[82:85]
	v_mfma_f32_16x16x32_bf16 v[70:73], v[176:179], v[232:235], v[70:73]
	v_mfma_f32_16x16x32_bf16 v[66:69], v[184:187], v[232:235], v[66:69]
	s_setprio 0
	s_setprio 1
	v_mfma_f32_16x16x32_bf16 v[118:121], v[180:183], v[212:215], v[118:121]
	v_mfma_f32_16x16x32_bf16 v[114:117], v[204:207], v[212:215], v[114:117]
	v_mfma_f32_16x16x32_bf16 v[102:105], v[180:183], v[220:223], v[102:105]
	v_mfma_f32_16x16x32_bf16 v[98:101], v[204:207], v[220:223], v[98:101]
	v_mfma_f32_16x16x32_bf16 v[86:89], v[180:183], v[228:231], v[86:89]
	v_mfma_f32_16x16x32_bf16 v[82:85], v[204:207], v[228:231], v[82:85]
	v_mfma_f32_16x16x32_bf16 v[70:73], v[180:183], v[236:239], v[70:73]
	v_mfma_f32_16x16x32_bf16 v[66:69], v[204:207], v[236:239], v[66:69]
	s_setprio 0
	s_barrier
	s_add_i32 s47, s47, s4
	v_lshl_add_u64 v[160:161], s[18:19], 0, v[148:149]
	s_mov_b32 m0, s47
	ds_read_b128 v[208:211], v163 offset:16384
	ds_read_b128 v[212:215], v163 offset:17408
	ds_read_b128 v[216:219], v163 offset:18432
	ds_read_b128 v[220:223], v163 offset:19456
	ds_read_b128 v[224:227], v163 offset:20480
	ds_read_b128 v[228:231], v163 offset:21504
	ds_read_b128 v[232:235], v163 offset:22528
	ds_read_b128 v[236:239], v163 offset:23552
	global_load_lds_dwordx4 v[160:161], off
	s_add_i32 m0, s47, 0x2000
	s_add_u32 s76, s18, 0x200000
	v_lshl_add_u64 v[240:241], s[18:19], 0, v[144:145]
	s_addc_u32 s77, s19, 0
	s_add_i32 s47, s80, s4
	global_load_lds_dwordx4 v[240:241], off
	v_lshl_add_u64 v[242:243], s[76:77], 0, v[148:149]
	s_mov_b32 m0, s47
	v_lshl_add_u64 v[244:245], s[62:63], 0, v[146:147]
	global_load_lds_dwordx4 v[242:243], off
	v_lshl_add_u64 v[242:243], s[76:77], 0, v[144:145]
	s_add_i32 m0, s47, 0x2000
	s_nop 0
	global_load_lds_dwordx4 v[242:243], off
	v_lshl_add_u64 v[242:243], s[62:63], 0, v[150:151]
	s_mov_b32 m0, s5
	s_nop 0
	global_load_lds_dwordx4 v[242:243], off
	s_mov_b32 m0, s30
	s_nop 0
	global_load_lds_dwordx4 v[244:245], off
	s_waitcnt vmcnt(8)
	s_waitcnt lgkmcnt(0)
	s_setprio 1
	s_barrier
; #define PG8_STAGE(bufoff, gbase, voff) do { _Pragma("unroll") for (int _i = 0; _i < 2; ++_i) \
;         __builtin_amdgcn_global_load_lds((const unsigned*)((const char*)(gbase) + (voff)[_i]), (PG8_LAS unsigned*)(lds + (bufoff) + ldsw + _i * 8192), 16, 0, 0); } while (0)
; #define PG8_LDA(dst, b, h) do { _Pragma("unroll") for (int m = 0; m < 4; ++m) _Pragma("unroll") for (int k = 0; k < 2; ++k) dst[m][k] = *(const PG8_LAS bf16x8*)(lds + PG8_SA(b, h) + aoff + m * 2048 + k * 1024); } while (0)
; #define PG8_LDB(dst, b, h) do { _Pragma("unroll") for (int n = 0; n < 2; ++n) _Pragma("unroll") for (int k = 0; k < 2; ++k) dst[n][k] = *(const PG8_LAS bf16x8*)(lds + PG8_SB(b, h) + boff + n * 2048 + k * 1024); } while (0)
; #define PG8_MMA(ai, bj, At, Bt) do { __builtin_amdgcn_s_setprio(1); _Pragma("unroll") for (int m = 0; m < 4; ++m) _Pragma("unroll") for (int n = 0; n < 2; ++n) _Pragma("unroll") for (int k = 0; k < 2; ++k) \
;         acc[ai][bj][m][n] = __builtin_amdgcn_mfma_f32_16x16x32_bf16(Bt[n][k], At[m][k], acc[ai][bj][m][n], 0, 0, 0); __builtin_amdgcn_s_setprio(0); } while (0)
; #define PG8_WAIT_V(n) asm volatile("s_waitcnt vmcnt(" #n ")" ::: "memory")
; #define PG8_WAIT_L(n) asm volatile("s_waitcnt lgkmcnt(" #n ")" ::: "memory")
; #define PG8_BAR __builtin_amdgcn_s_barrier()
; #define PG8_SCHED __builtin_amdgcn_sched_barrier(0)
; template <class Epi, class Sched, bool ALIGN_EPI = false, bool SP2 = false>
; __device__ __forceinline__ void gemm_phase(PG8_LAS unsigned char* lds, const Gemm g, const Sched& S, const Epi& E) {
;     ...
;             PG8_WAIT_V(8); PG8_WAIT_L(0); PG8_BAR; PG8_MMA(1, 0, At, B0); PG8_MMA(1, 1, At, B1); PG8_BAR; PG8_SCHED;
;             PG8_LDB(B0, 1, 0); PG8_LDB(B1, 1, 1); PG8_SCHED; PG8_LDA(At, 1, 0); PG8_STAGE(PG8_SA(0, 1), a2 + hstep, voffA);
;             PG8_WAIT_V(8); PG8_WAIT_L(0); PG8_BAR; PG8_MMA(0, 0, At, B0); PG8_MMA(0, 1, At, B1); PG8_BAR; PG8_SCHED;
	v_mfma_f32_16x16x32_bf16 v[62:65], v[156:159], v[208:211], v[62:65]
	v_mfma_f32_16x16x32_bf16 v[58:61], v[168:171], v[208:211], v[58:61]
	v_mfma_f32_16x16x32_bf16 v[46:49], v[156:159], v[216:219], v[46:49]
	v_mfma_f32_16x16x32_bf16 v[42:45], v[168:171], v[216:219], v[42:45]
	v_mfma_f32_16x16x32_bf16 v[30:33], v[156:159], v[224:227], v[30:33]
	v_mfma_f32_16x16x32_bf16 v[26:29], v[168:171], v[224:227], v[26:29]
	v_mfma_f32_16x16x32_bf16 v[14:17], v[156:159], v[232:235], v[14:17]
	v_mfma_f32_16x16x32_bf16 v[10:13], v[168:171], v[232:235], v[10:13]
	v_mfma_f32_16x16x32_bf16 v[62:65], v[164:167], v[212:215], v[62:65]
	v_mfma_f32_16x16x32_bf16 v[58:61], v[172:175], v[212:215], v[58:61]
	v_mfma_f32_16x16x32_bf16 v[46:49], v[164:167], v[220:223], v[46:49]
	v_mfma_f32_16x16x32_bf16 v[42:45], v[172:175], v[220:223], v[42:45]
	v_mfma_f32_16x16x32_bf16 v[30:33], v[164:167], v[228:231], v[30:33]
	v_mfma_f32_16x16x32_bf16 v[26:29], v[172:175], v[228:231], v[26:29]
	v_mfma_f32_16x16x32_bf16 v[14:17], v[164:167], v[236:239], v[14:17]
	v_mfma_f32_16x16x32_bf16 v[10:13], v[172:175], v[236:239], v[10:13]
	v_mfma_f32_16x16x32_bf16 v[54:57], v[176:179], v[208:211], v[54:57]
	v_mfma_f32_16x16x32_bf16 v[50:53], v[184:187], v[208:211], v[50:53]
	v_mfma_f32_16x16x32_bf16 v[38:41], v[176:179], v[216:219], v[38:41]
	v_mfma_f32_16x16x32_bf16 v[34:37], v[184:187], v[216:219], v[34:37]
	v_mfma_f32_16x16x32_bf16 v[22:25], v[176:179], v[224:227], v[22:25]
	v_mfma_f32_16x16x32_bf16 v[18:21], v[184:187], v[224:227], v[18:21]
	v_mfma_f32_16x16x32_bf16 v[6:9], v[176:179], v[232:235], v[6:9]
	v_mfma_f32_16x16x32_bf16 v[2:5], v[184:187], v[232:235], v[2:5]
	v_mfma_f32_16x16x32_bf16 v[54:57], v[180:183], v[212:215], v[54:57]
	v_mfma_f32_16x16x32_bf16 v[50:53], v[204:207], v[212:215], v[50:53]
	v_mfma_f32_16x16x32_bf16 v[38:41], v[180:183], v[220:223], v[38:41]
	v_mfma_f32_16x16x32_bf16 v[34:37], v[204:207], v[220:223], v[34:37]
	v_mfma_f32_16x16x32_bf16 v[22:25], v[180:183], v[228:231], v[22:25]
	v_mfma_f32_16x16x32_bf16 v[18:21], v[204:207], v[228:231], v[18:21]
	v_mfma_f32_16x16x32_bf16 v[6:9], v[180:183], v[236:239], v[6:9]
	v_mfma_f32_16x16x32_bf16 v[2:5], v[204:207], v[236:239], v[2:5]
	s_setprio 0
	s_barrier
	s_add_i32 s47, 0, 0x18000
	s_add_i32 s76, 0, 0x1c000
	v_add_u32_e32 v172, s47, v143
	v_add_u32_e32 v203, s76, v143
	ds_read_b128 v[156:159], v172
	ds_read_b128 v[164:167], v172 offset:1024
	ds_read_b128 v[168:171], v172 offset:2048
	ds_read_b128 v[172:175], v172 offset:3072
	ds_read_b128 v[176:179], v203
	ds_read_b128 v[180:183], v203 offset:1024
	ds_read_b128 v[184:187], v203 offset:2048
	ds_read_b128 v[204:207], v203 offset:3072
	s_add_u32 s62, s62, 0x200000
	s_addc_u32 s63, s63, 0
	s_mov_b32 m0, s57
	v_lshl_add_u64 v[246:247], s[62:63], 0, v[150:151]
	ds_read_b128 v[208:211], v163 offset:32768
	ds_read_b128 v[212:215], v163 offset:33792
	ds_read_b128 v[216:219], v163 offset:34816
	ds_read_b128 v[220:223], v163 offset:35840
	ds_read_b128 v[224:227], v163 offset:36864
	ds_read_b128 v[228:231], v163 offset:37888
	ds_read_b128 v[232:235], v163 offset:38912
	ds_read_b128 v[236:239], v163 offset:39936
	global_load_lds_dwordx4 v[246:247], off
	v_lshl_add_u64 v[246:247], s[62:63], 0, v[146:147]
	s_mov_b32 m0, s67
	s_nop 0
	global_load_lds_dwordx4 v[246:247], off
	s_waitcnt vmcnt(8)
	s_waitcnt lgkmcnt(0)
	s_setprio 1
	s_barrier
	v_mfma_f32_16x16x32_bf16 v[126:129], v[156:159], v[208:211], v[126:129]
	v_mfma_f32_16x16x32_bf16 v[122:125], v[168:171], v[208:211], v[122:125]
	v_mfma_f32_16x16x32_bf16 v[110:113], v[156:159], v[216:219], v[110:113]
	v_mfma_f32_16x16x32_bf16 v[106:109], v[168:171], v[216:219], v[106:109]
	v_mfma_f32_16x16x32_bf16 v[94:97], v[156:159], v[224:227], v[94:97]
	v_mfma_f32_16x16x32_bf16 v[90:93], v[168:171], v[224:227], v[90:93]
	v_mfma_f32_16x16x32_bf16 v[78:81], v[156:159], v[232:235], v[78:81]
	v_mfma_f32_16x16x32_bf16 v[74:77], v[168:171], v[232:235], v[74:77]
	s_setprio 0
	s_setprio 1
	v_mfma_f32_16x16x32_bf16 v[126:129], v[164:167], v[212:215], v[126:129]
	v_mfma_f32_16x16x32_bf16 v[122:125], v[172:175], v[212:215], v[122:125]
	v_mfma_f32_16x16x32_bf16 v[110:113], v[164:167], v[220:223], v[110:113]
	v_mfma_f32_16x16x32_bf16 v[106:109], v[172:175], v[220:223], v[106:109]
	v_mfma_f32_16x16x32_bf16 v[94:97], v[164:167], v[228:231], v[94:97]
	v_mfma_f32_16x16x32_bf16 v[90:93], v[172:175], v[228:231], v[90:93]
	v_mfma_f32_16x16x32_bf16 v[78:81], v[164:167], v[236:239], v[78:81]
	v_mfma_f32_16x16x32_bf16 v[74:77], v[172:175], v[236:239], v[74:77]
	s_setprio 0
	s_setprio 1
	v_mfma_f32_16x16x32_bf16 v[118:121], v[176:179], v[208:211], v[118:121]
	v_mfma_f32_16x16x32_bf16 v[114:117], v[184:187], v[208:211], v[114:117]
	v_mfma_f32_16x16x32_bf16 v[102:105], v[176:179], v[216:219], v[102:105]
	v_mfma_f32_16x16x32_bf16 v[98:101], v[184:187], v[216:219], v[98:101]
	v_mfma_f32_16x16x32_bf16 v[86:89], v[176:179], v[224:227], v[86:89]
	v_mfma_f32_16x16x32_bf16 v[82:85], v[184:187], v[224:227], v[82:85]
	v_mfma_f32_16x16x32_bf16 v[70:73], v[176:179], v[232:235], v[70:73]
	v_mfma_f32_16x16x32_bf16 v[66:69], v[184:187], v[232:235], v[66:69]
	s_setprio 0
	s_setprio 1
	v_mfma_f32_16x16x32_bf16 v[118:121], v[180:183], v[212:215], v[118:121]
	v_mfma_f32_16x16x32_bf16 v[114:117], v[204:207], v[212:215], v[114:117]
	v_mfma_f32_16x16x32_bf16 v[102:105], v[180:183], v[220:223], v[102:105]
	v_mfma_f32_16x16x32_bf16 v[98:101], v[204:207], v[220:223], v[98:101]
	v_mfma_f32_16x16x32_bf16 v[86:89], v[180:183], v[228:231], v[86:89]
	v_mfma_f32_16x16x32_bf16 v[82:85], v[204:207], v[228:231], v[82:85]
	v_mfma_f32_16x16x32_bf16 v[70:73], v[180:183], v[236:239], v[70:73]
	v_mfma_f32_16x16x32_bf16 v[66:69], v[204:207], v[236:239], v[66:69]
	s_setprio 0
	s_barrier
; #define PG8_STAGE(bufoff, gbase, voff) do { _Pragma("unroll") for (int _i = 0; _i < 2; ++_i) \
;         __builtin_amdgcn_global_load_lds((const unsigned*)((const char*)(gbase) + (voff)[_i]), (PG8_LAS unsigned*)(lds + (bufoff) + ldsw + _i * 8192), 16, 0, 0); } while (0)
; #define PG8_LDA(dst, b, h) do { _Pragma("unroll") for (int m = 0; m < 4; ++m) _Pragma("unroll") for (int k = 0; k < 2; ++k) dst[m][k] = *(const PG8_LAS bf16x8*)(lds + PG8_SA(b, h) + aoff + m * 2048 + k * 1024); } while (0)
; #define PG8_MMA(ai, bj, At, Bt) do { __builtin_amdgcn_s_setprio(1); _Pragma("unroll") for (int m = 0; m < 4; ++m) _Pragma("unroll") for (int n = 0; n < 2; ++n) _Pragma("unroll") for (int k = 0; k < 2; ++k) \
;         acc[ai][bj][m][n] = __builtin_amdgcn_mfma_f32_16x16x32_bf16(Bt[n][k], At[m][k], acc[ai][bj][m][n], 0, 0, 0); __builtin_amdgcn_s_setprio(0); } while (0)
; #define PG8_WAIT_V(n) asm volatile("s_waitcnt vmcnt(" #n ")" ::: "memory")
; #define PG8_WAIT_L(n) asm volatile("s_waitcnt lgkmcnt(" #n ")" ::: "memory")
; #define PG8_BAR __builtin_amdgcn_s_barrier()
; #define PG8_SCHED __builtin_amdgcn_sched_barrier(0)
; template <class Epi, class Sched, bool ALIGN_EPI = false, bool SP2 = false>
; __device__ __forceinline__ void gemm_phase(PG8_LAS unsigned char* lds, const Gemm g, const Sched& S, const Epi& E) {
;     ...
;             PG8_LDA(At, 1, 1); PG8_STAGE(PG8_SB(1, 0), b3, voffB); PG8_STAGE(PG8_SB(1, 1), b3 + hstep, voffB); PG8_STAGE(PG8_SA(1, 0), a3, voffA);
;             PG8_WAIT_V(8); PG8_WAIT_L(0); PG8_BAR; PG8_MMA(1, 0, At, B0); PG8_MMA(1, 1, At, B1); PG8_BAR; PG8_SCHED;
;     ...
;         if constexpr (ALIGN_EPI) { if (wr == 0) PG8_BAR; }
	s_add_i32 s47, s47, s4
	v_lshl_add_u64 v[160:161], v[160:161], 0, s[68:69]
	s_mov_b32 m0, s47
	ds_read_b128 v[208:211], v163 offset:49152
	ds_read_b128 v[212:215], v163 offset:50176
	ds_read_b128 v[216:219], v163 offset:51200
	ds_read_b128 v[220:223], v163 offset:52224
	ds_read_b128 v[224:227], v163 offset:53248
	ds_read_b128 v[228:231], v163 offset:54272
	ds_read_b128 v[232:235], v163 offset:55296
	ds_read_b128 v[236:239], v163 offset:56320
	global_load_lds_dwordx4 v[160:161], off
	s_add_i32 m0, s47, 0x2000
	s_add_u32 s18, s18, 0x200080
	v_lshl_add_u64 v[160:161], v[240:241], 0, s[68:69]
	s_addc_u32 s19, s19, 0
	s_add_i32 s47, s76, s4
	global_load_lds_dwordx4 v[160:161], off
	v_lshl_add_u64 v[160:161], s[18:19], 0, v[148:149]
	s_mov_b32 m0, s47
	s_nop 0
	global_load_lds_dwordx4 v[160:161], off
	v_lshl_add_u64 v[160:161], s[18:19], 0, v[144:145]
	s_add_i32 m0, s47, 0x2000
	s_nop 0
	global_load_lds_dwordx4 v[160:161], off
	v_lshl_add_u64 v[160:161], v[242:243], 0, s[68:69]
	s_mov_b32 m0, s1
	s_nop 0
	global_load_lds_dwordx4 v[160:161], off
	v_lshl_add_u64 v[160:161], v[244:245], 0, s[68:69]
	s_mov_b32 m0, s60
	s_nop 0
	global_load_lds_dwordx4 v[160:161], off
	s_nop 0
	s_waitcnt vmcnt(8)
	s_waitcnt lgkmcnt(0)
	s_setprio 1
	s_barrier
	v_mfma_f32_16x16x32_bf16 v[62:65], v[156:159], v[208:211], v[62:65]
	v_mfma_f32_16x16x32_bf16 v[58:61], v[168:171], v[208:211], v[58:61]
	v_mfma_f32_16x16x32_bf16 v[46:49], v[156:159], v[216:219], v[46:49]
	v_mfma_f32_16x16x32_bf16 v[42:45], v[168:171], v[216:219], v[42:45]
	v_mfma_f32_16x16x32_bf16 v[30:33], v[156:159], v[224:227], v[30:33]
	v_mfma_f32_16x16x32_bf16 v[26:29], v[168:171], v[224:227], v[26:29]
	v_mfma_f32_16x16x32_bf16 v[14:17], v[156:159], v[232:235], v[14:17]
	v_mfma_f32_16x16x32_bf16 v[10:13], v[168:171], v[232:235], v[10:13]
	v_mfma_f32_16x16x32_bf16 v[62:65], v[164:167], v[212:215], v[62:65]
	v_mfma_f32_16x16x32_bf16 v[58:61], v[172:175], v[212:215], v[58:61]
	v_mfma_f32_16x16x32_bf16 v[46:49], v[164:167], v[220:223], v[46:49]
	v_mfma_f32_16x16x32_bf16 v[42:45], v[172:175], v[220:223], v[42:45]
	v_mfma_f32_16x16x32_bf16 v[30:33], v[164:167], v[228:231], v[30:33]
	v_mfma_f32_16x16x32_bf16 v[26:29], v[172:175], v[228:231], v[26:29]
	v_mfma_f32_16x16x32_bf16 v[14:17], v[164:167], v[236:239], v[14:17]
	v_mfma_f32_16x16x32_bf16 v[10:13], v[172:175], v[236:239], v[10:13]
	v_mfma_f32_16x16x32_bf16 v[54:57], v[176:179], v[208:211], v[54:57]
	v_mfma_f32_16x16x32_bf16 v[50:53], v[184:187], v[208:211], v[50:53]
	v_mfma_f32_16x16x32_bf16 v[38:41], v[176:179], v[216:219], v[38:41]
	v_mfma_f32_16x16x32_bf16 v[34:37], v[184:187], v[216:219], v[34:37]
	v_mfma_f32_16x16x32_bf16 v[22:25], v[176:179], v[224:227], v[22:25]
	v_mfma_f32_16x16x32_bf16 v[18:21], v[184:187], v[224:227], v[18:21]
	v_mfma_f32_16x16x32_bf16 v[6:9], v[176:179], v[232:235], v[6:9]
	v_mfma_f32_16x16x32_bf16 v[2:5], v[184:187], v[232:235], v[2:5]
	v_mfma_f32_16x16x32_bf16 v[54:57], v[180:183], v[212:215], v[54:57]
	v_mfma_f32_16x16x32_bf16 v[50:53], v[204:207], v[212:215], v[50:53]
	v_mfma_f32_16x16x32_bf16 v[38:41], v[180:183], v[220:223], v[38:41]
	v_mfma_f32_16x16x32_bf16 v[34:37], v[204:207], v[220:223], v[34:37]
	v_mfma_f32_16x16x32_bf16 v[22:25], v[180:183], v[228:231], v[22:25]
	v_mfma_f32_16x16x32_bf16 v[18:21], v[204:207], v[228:231], v[18:21]
	v_mfma_f32_16x16x32_bf16 v[6:9], v[180:183], v[236:239], v[6:9]
	v_mfma_f32_16x16x32_bf16 v[2:5], v[204:207], v[236:239], v[2:5]
	s_setprio 0
	s_barrier
	s_add_i32 s46, s46, 2
	s_add_u32 s58, s58, 0x100
	s_addc_u32 s59, s59, 0
	s_add_u32 s78, s78, 0x100
	s_addc_u32 s79, s79, 0
	s_cmpk_gt_u32 s46, 0x7d
	s_cbranch_scc0 .LBB0_36
	s_and_b64 vcc, exec, s[12:13]
	s_cbranch_vccz .LBB0_39
	s_barrier

; #define PG8_STAGE(bufoff, gbase, voff) do { _Pragma("unroll") for (int _i = 0; _i < 2; ++_i) \
;         __builtin_amdgcn_global_load_lds((const unsigned*)((const char*)(gbase) + (voff)[_i]), (PG8_LAS unsigned*)(lds + (bufoff) + ldsw + _i * 8192), 16, 0, 0); } while (0)
; #define PG8_LDA(dst, b, h) do { _Pragma("unroll") for (int m = 0; m < 4; ++m) _Pragma("unroll") for (int k = 0; k < 2; ++k) dst[m][k] = *(const PG8_LAS bf16x8*)(lds + PG8_SA(b, h) + aoff + m * 2048 + k * 1024); } while (0)
; #define PG8_LDB(dst, b, h) do { _Pragma("unroll") for (int n = 0; n < 2; ++n) _Pragma("unroll") for (int k = 0; k < 2; ++k) dst[n][k] = *(const PG8_LAS bf16x8*)(lds + PG8_SB(b, h) + boff + n * 2048 + k * 1024); } while (0)
; #define PG8_MMA(ai, bj, At, Bt) do { __builtin_amdgcn_s_setprio(1); _Pragma("unroll") for (int m = 0; m < 4; ++m) _Pragma("unroll") for (int n = 0; n < 2; ++n) _Pragma("unroll") for (int k = 0; k < 2; ++k) \
;         acc[ai][bj][m][n] = __builtin_amdgcn_mfma_f32_16x16x32_bf16(Bt[n][k], At[m][k], acc[ai][bj][m][n], 0, 0, 0); __builtin_amdgcn_s_setprio(0); } while (0)
; #define PG8_WAIT_V(n) asm volatile("s_waitcnt vmcnt(" #n ")" ::: "memory")
; #define PG8_WAIT_L(n) asm volatile("s_waitcnt lgkmcnt(" #n ")" ::: "memory")
; template <class Epi, class Sched, bool ALIGN_EPI = false, bool SP2 = false>
; __device__ __forceinline__ void gemm_phase(PG8_LAS unsigned char* lds, const Gemm g, const Sched& S, const Epi& E) {
;     ...
;             const bool last = (t == nt - 2);
;             const char* a1 = cA + (size_t)(t + 1) * kstep;
;             const char* a2 = last ? nA : cA + (size_t)(t + 2) * kstep; const char* b2 = last ? nB : cB + (size_t)(t + 2) * kstep;
;             const char* a3 = a2 + kstep; const char* b3 = b2 + kstep;
;             if (last && has_next) S.a_ready(nxt);
;             if constexpr (SP2) {
;             PG8_LDB(B0, 0, 0); PG8_LDB(B1, 0, 1); PG8_SCHED; PG8_LDA(At, 0, 0); PG8_STAGE(PG8_SA(1, 1), a1 + hstep, voffA);
;             PG8_WAIT_V(8); PG8_WAIT_L(0); PG8_BAR; PG8_MMA(0, 0, At, B0); PG8_MMA(0, 1, At, B1); PG8_BAR; PG8_SCHED;
;             PG8_LDA(At, 0, 1); PG8_STAGE(PG8_SB(0, 0), b2, voffB); PG8_STAGE(PG8_SB(0, 1), b2 + hstep, voffB); PG8_STAGE(PG8_SA(0, 0), a2, voffA);
;             PG8_WAIT_V(8); PG8_WAIT_L(0); PG8_BAR; PG8_MMA(1, 0, At, B0); PG8_MMA(1, 1, At, B1); PG8_BAR; PG8_SCHED;
.LBB0_76:
	s_add_u32 s18, s0, 0xfff80080
	s_addc_u32 s19, s1, -1
	s_add_i32 s47, 0, 0x10000
	s_cmp_eq_u32 s46, 28
	s_cselect_b32 s59, s60, s19
	s_cselect_b32 s58, s73, s18
	v_add_u32_e32 v158, s47, v143
	s_cselect_b32 s19, s45, s79
	s_cselect_b32 s18, s84, s78
	s_add_i32 s80, 0, 0x14000
	ds_read_b128 v[162:165], v158
	ds_read_b128 v[166:169], v158 offset:1024
	ds_read_b128 v[170:173], v158 offset:2048
	ds_read_b128 v[174:177], v158 offset:3072
	v_add_u32_e32 v158, s80, v143
	ds_read_b128 v[178:181], v158
	ds_read_b128 v[182:185], v158 offset:1024
	ds_read_b128 v[204:207], v158 offset:2048
	ds_read_b128 v[208:211], v158 offset:3072
	v_lshl_add_u64 v[158:159], s[0:1], 0, v[154:155]
	s_add_i32 m0, s62, 0xc000
	ds_read_b128 v[212:215], v161
	ds_read_b128 v[216:219], v161 offset:1024
	ds_read_b128 v[220:223], v161 offset:2048
	ds_read_b128 v[224:227], v161 offset:3072
	ds_read_b128 v[228:231], v161 offset:4096
	ds_read_b128 v[232:235], v161 offset:5120
	ds_read_b128 v[236:239], v161 offset:6144
	ds_read_b128 v[240:243], v161 offset:7168
	global_load_lds_dwordx4 v[158:159], off
	v_lshl_add_u64 v[158:159], s[0:1], 0, v[156:157]
	s_add_i32 m0, s62, 0xe000
	s_nop 0
	global_load_lds_dwordx4 v[158:159], off
	s_nop 0
	s_waitcnt vmcnt(8)
	s_waitcnt lgkmcnt(0)
	s_setprio 1
	s_barrier
	v_mfma_f32_16x16x32_bf16 v[126:129], v[162:165], v[212:215], v[126:129]
	v_mfma_f32_16x16x32_bf16 v[122:125], v[170:173], v[212:215], v[122:125]
	v_mfma_f32_16x16x32_bf16 v[110:113], v[162:165], v[220:223], v[110:113]
	v_mfma_f32_16x16x32_bf16 v[106:109], v[170:173], v[220:223], v[106:109]
	v_mfma_f32_16x16x32_bf16 v[94:97], v[162:165], v[228:231], v[94:97]
	v_mfma_f32_16x16x32_bf16 v[90:93], v[170:173], v[228:231], v[90:93]
	v_mfma_f32_16x16x32_bf16 v[78:81], v[162:165], v[236:239], v[78:81]
	v_mfma_f32_16x16x32_bf16 v[74:77], v[170:173], v[236:239], v[74:77]
	s_setprio 0
	s_setprio 1
	v_mfma_f32_16x16x32_bf16 v[126:129], v[166:169], v[216:219], v[126:129]
	v_mfma_f32_16x16x32_bf16 v[122:125], v[174:177], v[216:219], v[122:125]
	v_mfma_f32_16x16x32_bf16 v[110:113], v[166:169], v[224:227], v[110:113]
	v_mfma_f32_16x16x32_bf16 v[106:109], v[174:177], v[224:227], v[106:109]
	v_mfma_f32_16x16x32_bf16 v[94:97], v[166:169], v[232:235], v[94:97]
	v_mfma_f32_16x16x32_bf16 v[90:93], v[174:177], v[232:235], v[90:93]
	v_mfma_f32_16x16x32_bf16 v[78:81], v[166:169], v[240:243], v[78:81]
	v_mfma_f32_16x16x32_bf16 v[74:77], v[174:177], v[240:243], v[74:77]
	s_setprio 0
	s_setprio 1
	v_mfma_f32_16x16x32_bf16 v[118:121], v[178:181], v[212:215], v[118:121]
	v_mfma_f32_16x16x32_bf16 v[114:117], v[204:207], v[212:215], v[114:117]
	v_mfma_f32_16x16x32_bf16 v[102:105], v[178:181], v[220:223], v[102:105]
	v_mfma_f32_16x16x32_bf16 v[98:101], v[204:207], v[220:223], v[98:101]
	v_mfma_f32_16x16x32_bf16 v[86:89], v[178:181], v[228:231], v[86:89]
	v_mfma_f32_16x16x32_bf16 v[82:85], v[204:207], v[228:231], v[82:85]
	v_mfma_f32_16x16x32_bf16 v[70:73], v[178:181], v[236:239], v[70:73]
	v_mfma_f32_16x16x32_bf16 v[66:69], v[204:207], v[236:239], v[66:69]
	s_setprio 0
	s_setprio 1
	v_mfma_f32_16x16x32_bf16 v[118:121], v[182:185], v[216:219], v[118:121]
	v_mfma_f32_16x16x32_bf16 v[114:117], v[208:211], v[216:219], v[114:117]
	v_mfma_f32_16x16x32_bf16 v[102:105], v[182:185], v[224:227], v[102:105]
	v_mfma_f32_16x16x32_bf16 v[98:101], v[208:211], v[224:227], v[98:101]
	v_mfma_f32_16x16x32_bf16 v[86:89], v[182:185], v[232:235], v[86:89]
	v_mfma_f32_16x16x32_bf16 v[82:85], v[208:211], v[232:235], v[82:85]
	v_mfma_f32_16x16x32_bf16 v[70:73], v[182:185], v[240:243], v[70:73]
	v_mfma_f32_16x16x32_bf16 v[66:69], v[208:211], v[240:243], v[66:69]
	s_setprio 0
	s_barrier
	s_add_i32 s47, s47, s54
	v_lshl_add_u64 v[158:159], s[18:19], 0, v[148:149]
	s_mov_b32 m0, s47
	ds_read_b128 v[212:215], v161 offset:16384
	ds_read_b128 v[216:219], v161 offset:17408
	ds_read_b128 v[220:223], v161 offset:18432
	ds_read_b128 v[224:227], v161 offset:19456
	ds_read_b128 v[228:231], v161 offset:20480
	ds_read_b128 v[232:235], v161 offset:21504
	ds_read_b128 v[236:239], v161 offset:22528
	ds_read_b128 v[240:243], v161 offset:23552
	global_load_lds_dwordx4 v[158:159], off
	s_add_i32 m0, s47, 0x2000
	s_add_u32 s76, s18, 0x80000
	v_lshl_add_u64 v[186:187], s[18:19], 0, v[144:145]
	s_addc_u32 s77, s19, 0
	s_add_i32 s47, s80, s54
	global_load_lds_dwordx4 v[186:187], off
	v_lshl_add_u64 v[244:245], s[76:77], 0, v[148:149]
	s_mov_b32 m0, s47
	v_lshl_add_u64 v[246:247], s[58:59], 0, v[146:147]
	global_load_lds_dwordx4 v[244:245], off
	v_lshl_add_u64 v[244:245], s[76:77], 0, v[144:145]
	s_add_i32 m0, s47, 0x2000
	s_nop 0
	global_load_lds_dwordx4 v[244:245], off
	v_lshl_add_u64 v[244:245], s[58:59], 0, v[150:151]
	s_mov_b32 m0, s62
	s_nop 0
	global_load_lds_dwordx4 v[244:245], off
	s_mov_b32 m0, s63
	s_nop 0
	global_load_lds_dwordx4 v[246:247], off
	s_waitcnt vmcnt(8)
	s_waitcnt lgkmcnt(0)
	s_setprio 1
	s_barrier
; #define PG8_STAGE(bufoff, gbase, voff) do { _Pragma("unroll") for (int _i = 0; _i < 2; ++_i) \
;         __builtin_amdgcn_global_load_lds((const unsigned*)((const char*)(gbase) + (voff)[_i]), (PG8_LAS unsigned*)(lds + (bufoff) + ldsw + _i * 8192), 16, 0, 0); } while (0)
; #define PG8_LDA(dst, b, h) do { _Pragma("unroll") for (int m = 0; m < 4; ++m) _Pragma("unroll") for (int k = 0; k < 2; ++k) dst[m][k] = *(const PG8_LAS bf16x8*)(lds + PG8_SA(b, h) + aoff + m * 2048 + k * 1024); } while (0)
; #define PG8_LDB(dst, b, h) do { _Pragma("unroll") for (int n = 0; n < 2; ++n) _Pragma("unroll") for (int k = 0; k < 2; ++k) dst[n][k] = *(const PG8_LAS bf16x8*)(lds + PG8_SB(b, h) + boff + n * 2048 + k * 1024); } while (0)
; #define PG8_MMA(ai, bj, At, Bt) do { __builtin_amdgcn_s_setprio(1); _Pragma("unroll") for (int m = 0; m < 4; ++m) _Pragma("unroll") for (int n = 0; n < 2; ++n) _Pragma("unroll") for (int k = 0; k < 2; ++k) \
;         acc[ai][bj][m][n] = __builtin_amdgcn_mfma_f32_16x16x32_bf16(Bt[n][k], At[m][k], acc[ai][bj][m][n], 0, 0, 0); __builtin_amdgcn_s_setprio(0); } while (0)
; #define PG8_WAIT_V(n) asm volatile("s_waitcnt vmcnt(" #n ")" ::: "memory")
; #define PG8_WAIT_L(n) asm volatile("s_waitcnt lgkmcnt(" #n ")" ::: "memory")
; #define PG8_BAR __builtin_amdgcn_s_barrier()
; #define PG8_SCHED __builtin_amdgcn_sched_barrier(0)
; template <class Epi, class Sched, bool ALIGN_EPI = false, bool SP2 = false>
; __device__ __forceinline__ void gemm_phase(PG8_LAS unsigned char* lds, const Gemm g, const Sched& S, const Epi& E) {
;     ...
;             PG8_WAIT_V(8); PG8_WAIT_L(0); PG8_BAR; PG8_MMA(1, 0, At, B0); PG8_MMA(1, 1, At, B1); PG8_BAR; PG8_SCHED;
;             PG8_LDB(B0, 1, 0); PG8_LDB(B1, 1, 1); PG8_SCHED; PG8_LDA(At, 1, 0); PG8_STAGE(PG8_SA(0, 1), a2 + hstep, voffA);
;             PG8_WAIT_V(8); PG8_WAIT_L(0); PG8_BAR; PG8_MMA(0, 0, At, B0); PG8_MMA(0, 1, At, B1); PG8_BAR; PG8_SCHED;
	v_mfma_f32_16x16x32_bf16 v[62:65], v[162:165], v[212:215], v[62:65]
	v_mfma_f32_16x16x32_bf16 v[58:61], v[170:173], v[212:215], v[58:61]
	v_mfma_f32_16x16x32_bf16 v[46:49], v[162:165], v[220:223], v[46:49]
	v_mfma_f32_16x16x32_bf16 v[42:45], v[170:173], v[220:223], v[42:45]
	v_mfma_f32_16x16x32_bf16 v[30:33], v[162:165], v[228:231], v[30:33]
	v_mfma_f32_16x16x32_bf16 v[26:29], v[170:173], v[228:231], v[26:29]
	v_mfma_f32_16x16x32_bf16 v[14:17], v[162:165], v[236:239], v[14:17]
	v_mfma_f32_16x16x32_bf16 v[10:13], v[170:173], v[236:239], v[10:13]
	v_mfma_f32_16x16x32_bf16 v[62:65], v[166:169], v[216:219], v[62:65]
	v_mfma_f32_16x16x32_bf16 v[58:61], v[174:177], v[216:219], v[58:61]
	v_mfma_f32_16x16x32_bf16 v[46:49], v[166:169], v[224:227], v[46:49]
	v_mfma_f32_16x16x32_bf16 v[42:45], v[174:177], v[224:227], v[42:45]
	v_mfma_f32_16x16x32_bf16 v[30:33], v[166:169], v[232:235], v[30:33]
	v_mfma_f32_16x16x32_bf16 v[26:29], v[174:177], v[232:235], v[26:29]
	v_mfma_f32_16x16x32_bf16 v[14:17], v[166:169], v[240:243], v[14:17]
	v_mfma_f32_16x16x32_bf16 v[10:13], v[174:177], v[240:243], v[10:13]
	v_mfma_f32_16x16x32_bf16 v[54:57], v[178:181], v[212:215], v[54:57]
	v_mfma_f32_16x16x32_bf16 v[50:53], v[204:207], v[212:215], v[50:53]
	v_mfma_f32_16x16x32_bf16 v[38:41], v[178:181], v[220:223], v[38:41]
	v_mfma_f32_16x16x32_bf16 v[34:37], v[204:207], v[220:223], v[34:37]
	v_mfma_f32_16x16x32_bf16 v[22:25], v[178:181], v[228:231], v[22:25]
	v_mfma_f32_16x16x32_bf16 v[18:21], v[204:207], v[228:231], v[18:21]
	v_mfma_f32_16x16x32_bf16 v[6:9], v[178:181], v[236:239], v[6:9]
	v_mfma_f32_16x16x32_bf16 v[2:5], v[204:207], v[236:239], v[2:5]
	v_mfma_f32_16x16x32_bf16 v[54:57], v[182:185], v[216:219], v[54:57]
	v_mfma_f32_16x16x32_bf16 v[50:53], v[208:211], v[216:219], v[50:53]
	v_mfma_f32_16x16x32_bf16 v[38:41], v[182:185], v[224:227], v[38:41]
	v_mfma_f32_16x16x32_bf16 v[34:37], v[208:211], v[224:227], v[34:37]
	v_mfma_f32_16x16x32_bf16 v[22:25], v[182:185], v[232:235], v[22:25]
	v_mfma_f32_16x16x32_bf16 v[18:21], v[208:211], v[232:235], v[18:21]
	v_mfma_f32_16x16x32_bf16 v[6:9], v[182:185], v[240:243], v[6:9]
	v_mfma_f32_16x16x32_bf16 v[2:5], v[208:211], v[240:243], v[2:5]
	s_setprio 0
	s_barrier
	s_add_i32 s47, 0, 0x18000
	s_add_i32 s76, 0, 0x1c000
	v_add_u32_e32 v174, s47, v143
	v_add_u32_e32 v203, s76, v143
	ds_read_b128 v[162:165], v174
	ds_read_b128 v[166:169], v174 offset:1024
	ds_read_b128 v[170:173], v174 offset:2048
	ds_read_b128 v[174:177], v174 offset:3072
	ds_read_b128 v[178:181], v203
	ds_read_b128 v[182:185], v203 offset:1024
	ds_read_b128 v[204:207], v203 offset:2048
	ds_read_b128 v[208:211], v203 offset:3072
	s_add_u32 s58, s58, 0x80000
	s_addc_u32 s59, s59, 0
	s_mov_b32 m0, s67
	v_lshl_add_u64 v[248:249], s[58:59], 0, v[150:151]
	ds_read_b128 v[212:215], v161 offset:32768
	ds_read_b128 v[216:219], v161 offset:33792
	ds_read_b128 v[220:223], v161 offset:34816
	ds_read_b128 v[224:227], v161 offset:35840
	ds_read_b128 v[228:231], v161 offset:36864
	ds_read_b128 v[232:235], v161 offset:37888
	ds_read_b128 v[236:239], v161 offset:38912
	ds_read_b128 v[240:243], v161 offset:39936
	global_load_lds_dwordx4 v[248:249], off
	v_lshl_add_u64 v[248:249], s[58:59], 0, v[146:147]
	s_mov_b32 m0, s4
	s_nop 0
	global_load_lds_dwordx4 v[248:249], off
	s_waitcnt vmcnt(8)
	s_waitcnt lgkmcnt(0)
	s_setprio 1
	s_barrier
	v_mfma_f32_16x16x32_bf16 v[126:129], v[162:165], v[212:215], v[126:129]
	v_mfma_f32_16x16x32_bf16 v[122:125], v[170:173], v[212:215], v[122:125]
	v_mfma_f32_16x16x32_bf16 v[110:113], v[162:165], v[220:223], v[110:113]
	v_mfma_f32_16x16x32_bf16 v[106:109], v[170:173], v[220:223], v[106:109]
	v_mfma_f32_16x16x32_bf16 v[94:97], v[162:165], v[228:231], v[94:97]
	v_mfma_f32_16x16x32_bf16 v[90:93], v[170:173], v[228:231], v[90:93]
	v_mfma_f32_16x16x32_bf16 v[78:81], v[162:165], v[236:239], v[78:81]
	v_mfma_f32_16x16x32_bf16 v[74:77], v[170:173], v[236:239], v[74:77]
	s_setprio 0
	s_setprio 1
	v_mfma_f32_16x16x32_bf16 v[126:129], v[166:169], v[216:219], v[126:129]
	v_mfma_f32_16x16x32_bf16 v[122:125], v[174:177], v[216:219], v[122:125]
	v_mfma_f32_16x16x32_bf16 v[110:113], v[166:169], v[224:227], v[110:113]
	v_mfma_f32_16x16x32_bf16 v[106:109], v[174:177], v[224:227], v[106:109]
	v_mfma_f32_16x16x32_bf16 v[94:97], v[166:169], v[232:235], v[94:97]
	v_mfma_f32_16x16x32_bf16 v[90:93], v[174:177], v[232:235], v[90:93]
	v_mfma_f32_16x16x32_bf16 v[78:81], v[166:169], v[240:243], v[78:81]
	v_mfma_f32_16x16x32_bf16 v[74:77], v[174:177], v[240:243], v[74:77]
	s_setprio 0
	s_setprio 1
	v_mfma_f32_16x16x32_bf16 v[118:121], v[178:181], v[212:215], v[118:121]
	v_mfma_f32_16x16x32_bf16 v[114:117], v[204:207], v[212:215], v[114:117]
	v_mfma_f32_16x16x32_bf16 v[102:105], v[178:181], v[220:223], v[102:105]
	v_mfma_f32_16x16x32_bf16 v[98:101], v[204:207], v[220:223], v[98:101]
	v_mfma_f32_16x16x32_bf16 v[86:89], v[178:181], v[228:231], v[86:89]
	v_mfma_f32_16x16x32_bf16 v[82:85], v[204:207], v[228:231], v[82:85]
	v_mfma_f32_16x16x32_bf16 v[70:73], v[178:181], v[236:239], v[70:73]
	v_mfma_f32_16x16x32_bf16 v[66:69], v[204:207], v[236:239], v[66:69]
	s_setprio 0
	s_setprio 1
	v_mfma_f32_16x16x32_bf16 v[118:121], v[182:185], v[216:219], v[118:121]
	v_mfma_f32_16x16x32_bf16 v[114:117], v[208:211], v[216:219], v[114:117]
	v_mfma_f32_16x16x32_bf16 v[102:105], v[182:185], v[224:227], v[102:105]
	v_mfma_f32_16x16x32_bf16 v[98:101], v[208:211], v[224:227], v[98:101]
	v_mfma_f32_16x16x32_bf16 v[86:89], v[182:185], v[232:235], v[86:89]
	v_mfma_f32_16x16x32_bf16 v[82:85], v[208:211], v[232:235], v[82:85]
	v_mfma_f32_16x16x32_bf16 v[70:73], v[182:185], v[240:243], v[70:73]
	v_mfma_f32_16x16x32_bf16 v[66:69], v[208:211], v[240:243], v[66:69]
	s_setprio 0
	s_barrier
; #define PG8_STAGE(bufoff, gbase, voff) do { _Pragma("unroll") for (int _i = 0; _i < 2; ++_i) \
;         __builtin_amdgcn_global_load_lds((const unsigned*)((const char*)(gbase) + (voff)[_i]), (PG8_LAS unsigned*)(lds + (bufoff) + ldsw + _i * 8192), 16, 0, 0); } while (0)
; #define PG8_LDA(dst, b, h) do { _Pragma("unroll") for (int m = 0; m < 4; ++m) _Pragma("unroll") for (int k = 0; k < 2; ++k) dst[m][k] = *(const PG8_LAS bf16x8*)(lds + PG8_SA(b, h) + aoff + m * 2048 + k * 1024); } while (0)
; #define PG8_MMA(ai, bj, At, Bt) do { __builtin_amdgcn_s_setprio(1); _Pragma("unroll") for (int m = 0; m < 4; ++m) _Pragma("unroll") for (int n = 0; n < 2; ++n) _Pragma("unroll") for (int k = 0; k < 2; ++k) \
;         acc[ai][bj][m][n] = __builtin_amdgcn_mfma_f32_16x16x32_bf16(Bt[n][k], At[m][k], acc[ai][bj][m][n], 0, 0, 0); __builtin_amdgcn_s_setprio(0); } while (0)
; #define PG8_WAIT_V(n) asm volatile("s_waitcnt vmcnt(" #n ")" ::: "memory")
; #define PG8_WAIT_L(n) asm volatile("s_waitcnt lgkmcnt(" #n ")" ::: "memory")
; #define PG8_BAR __builtin_amdgcn_s_barrier()
; #define PG8_SCHED __builtin_amdgcn_sched_barrier(0)
; template <class Epi, class Sched, bool ALIGN_EPI = false, bool SP2 = false>
; __device__ __forceinline__ void gemm_phase(PG8_LAS unsigned char* lds, const Gemm g, const Sched& S, const Epi& E) {
;     ...
;             PG8_LDA(At, 1, 1); PG8_STAGE(PG8_SB(1, 0), b3, voffB); PG8_STAGE(PG8_SB(1, 1), b3 + hstep, voffB); PG8_STAGE(PG8_SA(1, 0), a3, voffA);
;             PG8_WAIT_V(8); PG8_WAIT_L(0); PG8_BAR; PG8_MMA(1, 0, At, B0); PG8_MMA(1, 1, At, B1); PG8_BAR; PG8_SCHED;
;     ...
;         if constexpr (ALIGN_EPI) { if (wr == 0) PG8_BAR; }
	s_add_i32 s47, s47, s54
	v_lshl_add_u64 v[158:159], v[158:159], 0, s[68:69]
	s_mov_b32 m0, s47
	ds_read_b128 v[212:215], v161 offset:49152
	ds_read_b128 v[216:219], v161 offset:50176
	ds_read_b128 v[220:223], v161 offset:51200
	ds_read_b128 v[224:227], v161 offset:52224
	ds_read_b128 v[228:231], v161 offset:53248
	ds_read_b128 v[232:235], v161 offset:54272
	ds_read_b128 v[236:239], v161 offset:55296
	ds_read_b128 v[240:243], v161 offset:56320
	global_load_lds_dwordx4 v[158:159], off
	s_add_i32 m0, s47, 0x2000
	s_add_u32 s18, s18, 0x80080
	v_lshl_add_u64 v[158:159], v[186:187], 0, s[68:69]
	s_addc_u32 s19, s19, 0
	s_add_i32 s47, s76, s54
	global_load_lds_dwordx4 v[158:159], off
	v_lshl_add_u64 v[158:159], s[18:19], 0, v[148:149]
	s_mov_b32 m0, s47
	s_nop 0
	global_load_lds_dwordx4 v[158:159], off
	v_lshl_add_u64 v[158:159], s[18:19], 0, v[144:145]
	s_add_i32 m0, s47, 0x2000
	s_nop 0
	global_load_lds_dwordx4 v[158:159], off
	v_lshl_add_u64 v[158:159], v[244:245], 0, s[68:69]
	s_mov_b32 m0, s5
	s_nop 0
	global_load_lds_dwordx4 v[158:159], off
	v_lshl_add_u64 v[158:159], v[246:247], 0, s[68:69]
	s_mov_b32 m0, s57
	s_nop 0
	global_load_lds_dwordx4 v[158:159], off
	s_nop 0
	s_waitcnt vmcnt(8)
	s_waitcnt lgkmcnt(0)
	s_setprio 1
	s_barrier
	v_mfma_f32_16x16x32_bf16 v[62:65], v[162:165], v[212:215], v[62:65]
	v_mfma_f32_16x16x32_bf16 v[58:61], v[170:173], v[212:215], v[58:61]
	v_mfma_f32_16x16x32_bf16 v[46:49], v[162:165], v[220:223], v[46:49]
	v_mfma_f32_16x16x32_bf16 v[42:45], v[170:173], v[220:223], v[42:45]
	v_mfma_f32_16x16x32_bf16 v[30:33], v[162:165], v[228:231], v[30:33]
	v_mfma_f32_16x16x32_bf16 v[26:29], v[170:173], v[228:231], v[26:29]
	v_mfma_f32_16x16x32_bf16 v[14:17], v[162:165], v[236:239], v[14:17]
	v_mfma_f32_16x16x32_bf16 v[10:13], v[170:173], v[236:239], v[10:13]
	v_mfma_f32_16x16x32_bf16 v[62:65], v[166:169], v[216:219], v[62:65]
	v_mfma_f32_16x16x32_bf16 v[58:61], v[174:177], v[216:219], v[58:61]
	v_mfma_f32_16x16x32_bf16 v[46:49], v[166:169], v[224:227], v[46:49]
	v_mfma_f32_16x16x32_bf16 v[42:45], v[174:177], v[224:227], v[42:45]
	v_mfma_f32_16x16x32_bf16 v[30:33], v[166:169], v[232:235], v[30:33]
	v_mfma_f32_16x16x32_bf16 v[26:29], v[174:177], v[232:235], v[26:29]
	v_mfma_f32_16x16x32_bf16 v[14:17], v[166:169], v[240:243], v[14:17]
	v_mfma_f32_16x16x32_bf16 v[10:13], v[174:177], v[240:243], v[10:13]
	v_mfma_f32_16x16x32_bf16 v[54:57], v[178:181], v[212:215], v[54:57]
	v_mfma_f32_16x16x32_bf16 v[50:53], v[204:207], v[212:215], v[50:53]
	v_mfma_f32_16x16x32_bf16 v[38:41], v[178:181], v[220:223], v[38:41]
	v_mfma_f32_16x16x32_bf16 v[34:37], v[204:207], v[220:223], v[34:37]
	v_mfma_f32_16x16x32_bf16 v[22:25], v[178:181], v[228:231], v[22:25]
	v_mfma_f32_16x16x32_bf16 v[18:21], v[204:207], v[228:231], v[18:21]
	v_mfma_f32_16x16x32_bf16 v[6:9], v[178:181], v[236:239], v[6:9]
	v_mfma_f32_16x16x32_bf16 v[2:5], v[204:207], v[236:239], v[2:5]
	v_mfma_f32_16x16x32_bf16 v[54:57], v[182:185], v[216:219], v[54:57]
	v_mfma_f32_16x16x32_bf16 v[50:53], v[208:211], v[216:219], v[50:53]
	v_mfma_f32_16x16x32_bf16 v[38:41], v[182:185], v[224:227], v[38:41]
	v_mfma_f32_16x16x32_bf16 v[34:37], v[208:211], v[224:227], v[34:37]
	v_mfma_f32_16x16x32_bf16 v[22:25], v[182:185], v[232:235], v[22:25]
	v_mfma_f32_16x16x32_bf16 v[18:21], v[208:211], v[232:235], v[18:21]
	v_mfma_f32_16x16x32_bf16 v[6:9], v[182:185], v[240:243], v[6:9]
	v_mfma_f32_16x16x32_bf16 v[2:5], v[208:211], v[240:243], v[2:5]
	s_setprio 0
	s_barrier
	s_add_i32 s46, s46, 2
	s_add_u32 s0, s0, 0x100
	s_addc_u32 s1, s1, 0
	s_add_u32 s78, s78, 0x100
	s_addc_u32 s79, s79, 0
	s_cmp_gt_u32 s46, 29
	s_cbranch_scc0 .LBB0_76
	s_and_b64 vcc, exec, s[42:43]
	s_cbranch_vccz .LBB0_79
	s_barrier

; #define PG8_STAGE(bufoff, gbase, voff) do { _Pragma("unroll") for (int _i = 0; _i < 2; ++_i) \
;         __builtin_amdgcn_global_load_lds((const unsigned*)((const char*)(gbase) + (voff)[_i]), (PG8_LAS unsigned*)(lds + (bufoff) + ldsw + _i * 8192), 16, 0, 0); } while (0)
; #define PG8_LDA(dst, b, h) do { _Pragma("unroll") for (int m = 0; m < 4; ++m) _Pragma("unroll") for (int k = 0; k < 2; ++k) dst[m][k] = *(const PG8_LAS bf16x8*)(lds + PG8_SA(b, h) + aoff + m * 2048 + k * 1024); } while (0)
; #define PG8_LDB(dst, b, h) do { _Pragma("unroll") for (int n = 0; n < 2; ++n) _Pragma("unroll") for (int k = 0; k < 2; ++k) dst[n][k] = *(const PG8_LAS bf16x8*)(lds + PG8_SB(b, h) + boff + n * 2048 + k * 1024); } while (0)
; #define PG8_MMA(ai, bj, At, Bt) do { __builtin_amdgcn_s_setprio(1); _Pragma("unroll") for (int m = 0; m < 4; ++m) _Pragma("unroll") for (int n = 0; n < 2; ++n) _Pragma("unroll") for (int k = 0; k < 2; ++k) \
;         acc[ai][bj][m][n] = __builtin_amdgcn_mfma_f32_16x16x32_bf16(Bt[n][k], At[m][k], acc[ai][bj][m][n], 0, 0, 0); __builtin_amdgcn_s_setprio(0); } while (0)
; #define PG8_WAIT_V(n) asm volatile("s_waitcnt vmcnt(" #n ")" ::: "memory")
; #define PG8_WAIT_L(n) asm volatile("s_waitcnt lgkmcnt(" #n ")" ::: "memory")
; template <class Epi, class Sched, bool ALIGN_EPI = false, bool SP2 = false>
; __device__ __forceinline__ void gemm_phase(PG8_LAS unsigned char* lds, const Gemm g, const Sched& S, const Epi& E) {
;     ...
;             const bool last = (t == nt - 2);
;             const char* a1 = cA + (size_t)(t + 1) * kstep;
;             const char* a2 = last ? nA : cA + (size_t)(t + 2) * kstep; const char* b2 = last ? nB : cB + (size_t)(t + 2) * kstep;
;             const char* a3 = a2 + kstep; const char* b3 = b2 + kstep;
;             if (last && has_next) S.a_ready(nxt);
;             if constexpr (SP2) {
;             PG8_LDB(B0, 0, 0); PG8_LDB(B1, 0, 1); PG8_SCHED; PG8_LDA(At, 0, 0); PG8_STAGE(PG8_SA(1, 1), a1 + hstep, voffA);
;             PG8_WAIT_V(8); PG8_WAIT_L(0); PG8_BAR; PG8_MMA(0, 0, At, B0); PG8_MMA(0, 1, At, B1); PG8_BAR; PG8_SCHED;
;             PG8_LDA(At, 0, 1); PG8_STAGE(PG8_SB(0, 0), b2, voffB); PG8_STAGE(PG8_SB(0, 1), b2 + hstep, voffB); PG8_STAGE(PG8_SA(0, 0), a2, voffA);
;             PG8_WAIT_V(8); PG8_WAIT_L(0); PG8_BAR; PG8_MMA(1, 0, At, B0); PG8_MMA(1, 1, At, B1); PG8_BAR; PG8_SCHED;
.LBB0_98:
	s_add_u32 s40, vcc_lo, 0xfff80080
	s_addc_u32 s41, vcc_hi, -1
	s_add_i32 s47, 0, 0x10000
	s_cmp_eq_u32 s46, 28
	s_cselect_b32 s59, s97, s41
	s_cselect_b32 s58, s84, s40
	s_cselect_b32 s41, s85, s79
	s_cselect_b32 s40, s95, s78
	s_add_i32 s80, 0, 0x14000
	v_add_u32_e32 v170, s47, v143
	v_add_u32_e32 v186, s80, v143
	ds_read_b128 v[156:159], v170
	ds_read_b128 v[162:165], v170 offset:1024
	ds_read_b128 v[166:169], v170 offset:2048
	ds_read_b128 v[170:173], v170 offset:3072
	ds_read_b128 v[174:177], v186
	ds_read_b128 v[178:181], v186 offset:1024
	ds_read_b128 v[182:185], v186 offset:2048
	ds_read_b128 v[204:207], v186 offset:3072
	v_lshl_add_u64 v[186:187], vcc, 0, v[152:153]
	s_add_i32 m0, s5, 0xc000
	ds_read_b128 v[208:211], v161
	ds_read_b128 v[212:215], v161 offset:1024
	ds_read_b128 v[216:219], v161 offset:2048
	ds_read_b128 v[220:223], v161 offset:3072
	ds_read_b128 v[224:227], v161 offset:4096
	ds_read_b128 v[228:231], v161 offset:5120
	ds_read_b128 v[232:235], v161 offset:6144
	ds_read_b128 v[236:239], v161 offset:7168
	global_load_lds_dwordx4 v[186:187], off
	v_lshl_add_u64 v[186:187], vcc, 0, v[154:155]
	s_add_i32 m0, s5, 0xe000
	s_nop 0
	global_load_lds_dwordx4 v[186:187], off
	s_waitcnt vmcnt(8)
	s_waitcnt lgkmcnt(0)
	s_setprio 1
	s_barrier
	v_mfma_f32_16x16x32_bf16 v[126:129], v[156:159], v[208:211], v[126:129]
	v_mfma_f32_16x16x32_bf16 v[122:125], v[166:169], v[208:211], v[122:125]
	v_mfma_f32_16x16x32_bf16 v[110:113], v[156:159], v[216:219], v[110:113]
	v_mfma_f32_16x16x32_bf16 v[106:109], v[166:169], v[216:219], v[106:109]
	v_mfma_f32_16x16x32_bf16 v[94:97], v[156:159], v[224:227], v[94:97]
	v_mfma_f32_16x16x32_bf16 v[90:93], v[166:169], v[224:227], v[90:93]
	v_mfma_f32_16x16x32_bf16 v[78:81], v[156:159], v[232:235], v[78:81]
	v_mfma_f32_16x16x32_bf16 v[74:77], v[166:169], v[232:235], v[74:77]
	s_setprio 0
	s_setprio 1
	v_mfma_f32_16x16x32_bf16 v[126:129], v[162:165], v[212:215], v[126:129]
	v_mfma_f32_16x16x32_bf16 v[122:125], v[170:173], v[212:215], v[122:125]
	v_mfma_f32_16x16x32_bf16 v[110:113], v[162:165], v[220:223], v[110:113]
	v_mfma_f32_16x16x32_bf16 v[106:109], v[170:173], v[220:223], v[106:109]
	v_mfma_f32_16x16x32_bf16 v[94:97], v[162:165], v[228:231], v[94:97]
	v_mfma_f32_16x16x32_bf16 v[90:93], v[170:173], v[228:231], v[90:93]
	v_mfma_f32_16x16x32_bf16 v[78:81], v[162:165], v[236:239], v[78:81]
	v_mfma_f32_16x16x32_bf16 v[74:77], v[170:173], v[236:239], v[74:77]
	s_setprio 0
	s_setprio 1
	v_mfma_f32_16x16x32_bf16 v[118:121], v[174:177], v[208:211], v[118:121]
	v_mfma_f32_16x16x32_bf16 v[114:117], v[182:185], v[208:211], v[114:117]
	v_mfma_f32_16x16x32_bf16 v[102:105], v[174:177], v[216:219], v[102:105]
	v_mfma_f32_16x16x32_bf16 v[98:101], v[182:185], v[216:219], v[98:101]
	v_mfma_f32_16x16x32_bf16 v[86:89], v[174:177], v[224:227], v[86:89]
	v_mfma_f32_16x16x32_bf16 v[82:85], v[182:185], v[224:227], v[82:85]
	v_mfma_f32_16x16x32_bf16 v[70:73], v[174:177], v[232:235], v[70:73]
	v_mfma_f32_16x16x32_bf16 v[66:69], v[182:185], v[232:235], v[66:69]
	s_setprio 0
	s_setprio 1
	v_mfma_f32_16x16x32_bf16 v[118:121], v[178:181], v[212:215], v[118:121]
	v_mfma_f32_16x16x32_bf16 v[114:117], v[204:207], v[212:215], v[114:117]
	v_mfma_f32_16x16x32_bf16 v[102:105], v[178:181], v[220:223], v[102:105]
	v_mfma_f32_16x16x32_bf16 v[98:101], v[204:207], v[220:223], v[98:101]
	v_mfma_f32_16x16x32_bf16 v[86:89], v[178:181], v[228:231], v[86:89]
	v_mfma_f32_16x16x32_bf16 v[82:85], v[204:207], v[228:231], v[82:85]
	v_mfma_f32_16x16x32_bf16 v[70:73], v[178:181], v[236:239], v[70:73]
	v_mfma_f32_16x16x32_bf16 v[66:69], v[204:207], v[236:239], v[66:69]
	s_setprio 0
	s_barrier
	s_add_i32 s47, s47, s4
	v_lshl_add_u64 v[186:187], s[40:41], 0, v[148:149]
	s_mov_b32 m0, s47
	ds_read_b128 v[208:211], v161 offset:16384
	ds_read_b128 v[212:215], v161 offset:17408
	ds_read_b128 v[216:219], v161 offset:18432
	ds_read_b128 v[220:223], v161 offset:19456
	ds_read_b128 v[224:227], v161 offset:20480
	ds_read_b128 v[228:231], v161 offset:21504
	ds_read_b128 v[232:235], v161 offset:22528
	ds_read_b128 v[236:239], v161 offset:23552
	global_load_lds_dwordx4 v[186:187], off
	s_add_i32 m0, s47, 0x2000
	s_add_u32 s76, s40, 0x80000
	v_lshl_add_u64 v[240:241], s[40:41], 0, v[144:145]
	s_addc_u32 s77, s41, 0
	s_add_i32 s47, s80, s4
	global_load_lds_dwordx4 v[240:241], off
	v_lshl_add_u64 v[242:243], s[76:77], 0, v[148:149]
	s_mov_b32 m0, s47
	v_lshl_add_u64 v[244:245], s[58:59], 0, v[146:147]
	global_load_lds_dwordx4 v[242:243], off
	v_lshl_add_u64 v[242:243], s[76:77], 0, v[144:145]
	s_add_i32 m0, s47, 0x2000
	s_nop 0
	global_load_lds_dwordx4 v[242:243], off
	v_lshl_add_u64 v[242:243], s[58:59], 0, v[150:151]
	s_mov_b32 m0, s5
	s_nop 0
	global_load_lds_dwordx4 v[242:243], off
	s_mov_b32 m0, s30
	s_nop 0
	global_load_lds_dwordx4 v[244:245], off
	s_waitcnt vmcnt(8)
	s_waitcnt lgkmcnt(0)
	s_setprio 1
	s_barrier
; #define PG8_STAGE(bufoff, gbase, voff) do { _Pragma("unroll") for (int _i = 0; _i < 2; ++_i) \
;         __builtin_amdgcn_global_load_lds((const unsigned*)((const char*)(gbase) + (voff)[_i]), (PG8_LAS unsigned*)(lds + (bufoff) + ldsw + _i * 8192), 16, 0, 0); } while (0)
; #define PG8_LDA(dst, b, h) do { _Pragma("unroll") for (int m = 0; m < 4; ++m) _Pragma("unroll") for (int k = 0; k < 2; ++k) dst[m][k] = *(const PG8_LAS bf16x8*)(lds + PG8_SA(b, h) + aoff + m * 2048 + k * 1024); } while (0)
; #define PG8_LDB(dst, b, h) do { _Pragma("unroll") for (int n = 0; n < 2; ++n) _Pragma("unroll") for (int k = 0; k < 2; ++k) dst[n][k] = *(const PG8_LAS bf16x8*)(lds + PG8_SB(b, h) + boff + n * 2048 + k * 1024); } while (0)
; #define PG8_MMA(ai, bj, At, Bt) do { __builtin_amdgcn_s_setprio(1); _Pragma("unroll") for (int m = 0; m < 4; ++m) _Pragma("unroll") for (int n = 0; n < 2; ++n) _Pragma("unroll") for (int k = 0; k < 2; ++k) \
;         acc[ai][bj][m][n] = __builtin_amdgcn_mfma_f32_16x16x32_bf16(Bt[n][k], At[m][k], acc[ai][bj][m][n], 0, 0, 0); __builtin_amdgcn_s_setprio(0); } while (0)
; #define PG8_WAIT_V(n) asm volatile("s_waitcnt vmcnt(" #n ")" ::: "memory")
; #define PG8_WAIT_L(n) asm volatile("s_waitcnt lgkmcnt(" #n ")" ::: "memory")
; #define PG8_BAR __builtin_amdgcn_s_barrier()
; #define PG8_SCHED __builtin_amdgcn_sched_barrier(0)
; template <class Epi, class Sched, bool ALIGN_EPI = false, bool SP2 = false>
; __device__ __forceinline__ void gemm_phase(PG8_LAS unsigned char* lds, const Gemm g, const Sched& S, const Epi& E) {
;     ...
;             PG8_WAIT_V(8); PG8_WAIT_L(0); PG8_BAR; PG8_MMA(1, 0, At, B0); PG8_MMA(1, 1, At, B1); PG8_BAR; PG8_SCHED;
;             PG8_LDB(B0, 1, 0); PG8_LDB(B1, 1, 1); PG8_SCHED; PG8_LDA(At, 1, 0); PG8_STAGE(PG8_SA(0, 1), a2 + hstep, voffA);
;             PG8_WAIT_V(8); PG8_WAIT_L(0); PG8_BAR; PG8_MMA(0, 0, At, B0); PG8_MMA(0, 1, At, B1); PG8_BAR; PG8_SCHED;
	v_mfma_f32_16x16x32_bf16 v[62:65], v[156:159], v[208:211], v[62:65]
	v_mfma_f32_16x16x32_bf16 v[58:61], v[166:169], v[208:211], v[58:61]
	v_mfma_f32_16x16x32_bf16 v[46:49], v[156:159], v[216:219], v[46:49]
	v_mfma_f32_16x16x32_bf16 v[42:45], v[166:169], v[216:219], v[42:45]
	v_mfma_f32_16x16x32_bf16 v[30:33], v[156:159], v[224:227], v[30:33]
	v_mfma_f32_16x16x32_bf16 v[26:29], v[166:169], v[224:227], v[26:29]
	v_mfma_f32_16x16x32_bf16 v[14:17], v[156:159], v[232:235], v[14:17]
	v_mfma_f32_16x16x32_bf16 v[10:13], v[166:169], v[232:235], v[10:13]
	v_mfma_f32_16x16x32_bf16 v[62:65], v[162:165], v[212:215], v[62:65]
	v_mfma_f32_16x16x32_bf16 v[58:61], v[170:173], v[212:215], v[58:61]
	v_mfma_f32_16x16x32_bf16 v[46:49], v[162:165], v[220:223], v[46:49]
	v_mfma_f32_16x16x32_bf16 v[42:45], v[170:173], v[220:223], v[42:45]
	v_mfma_f32_16x16x32_bf16 v[30:33], v[162:165], v[228:231], v[30:33]
	v_mfma_f32_16x16x32_bf16 v[26:29], v[170:173], v[228:231], v[26:29]
	v_mfma_f32_16x16x32_bf16 v[14:17], v[162:165], v[236:239], v[14:17]
	v_mfma_f32_16x16x32_bf16 v[10:13], v[170:173], v[236:239], v[10:13]
	v_mfma_f32_16x16x32_bf16 v[54:57], v[174:177], v[208:211], v[54:57]
	v_mfma_f32_16x16x32_bf16 v[50:53], v[182:185], v[208:211], v[50:53]
	v_mfma_f32_16x16x32_bf16 v[38:41], v[174:177], v[216:219], v[38:41]
	v_mfma_f32_16x16x32_bf16 v[34:37], v[182:185], v[216:219], v[34:37]
	v_mfma_f32_16x16x32_bf16 v[22:25], v[174:177], v[224:227], v[22:25]
	v_mfma_f32_16x16x32_bf16 v[18:21], v[182:185], v[224:227], v[18:21]
	v_mfma_f32_16x16x32_bf16 v[6:9], v[174:177], v[232:235], v[6:9]
	v_mfma_f32_16x16x32_bf16 v[2:5], v[182:185], v[232:235], v[2:5]
	v_mfma_f32_16x16x32_bf16 v[54:57], v[178:181], v[212:215], v[54:57]
	v_mfma_f32_16x16x32_bf16 v[50:53], v[204:207], v[212:215], v[50:53]
	v_mfma_f32_16x16x32_bf16 v[38:41], v[178:181], v[220:223], v[38:41]
	v_mfma_f32_16x16x32_bf16 v[34:37], v[204:207], v[220:223], v[34:37]
	v_mfma_f32_16x16x32_bf16 v[22:25], v[178:181], v[228:231], v[22:25]
	v_mfma_f32_16x16x32_bf16 v[18:21], v[204:207], v[228:231], v[18:21]
	v_mfma_f32_16x16x32_bf16 v[6:9], v[178:181], v[236:239], v[6:9]
	v_mfma_f32_16x16x32_bf16 v[2:5], v[204:207], v[236:239], v[2:5]
	s_setprio 0
	s_barrier
	s_add_i32 s47, 0, 0x18000
	s_add_i32 s76, 0, 0x1c000
	v_add_u32_e32 v170, s47, v143
	v_add_u32_e32 v203, s76, v143
	ds_read_b128 v[156:159], v170
	ds_read_b128 v[162:165], v170 offset:1024
	ds_read_b128 v[166:169], v170 offset:2048
	ds_read_b128 v[170:173], v170 offset:3072
	ds_read_b128 v[174:177], v203
	ds_read_b128 v[178:181], v203 offset:1024
	ds_read_b128 v[182:185], v203 offset:2048
	ds_read_b128 v[204:207], v203 offset:3072
	s_add_u32 s58, s58, 0x80000
	s_addc_u32 s59, s59, 0
	s_mov_b32 m0, s34
	v_lshl_add_u64 v[246:247], s[58:59], 0, v[150:151]
	ds_read_b128 v[208:211], v161 offset:32768
	ds_read_b128 v[212:215], v161 offset:33792
	ds_read_b128 v[216:219], v161 offset:34816
	ds_read_b128 v[220:223], v161 offset:35840
	ds_read_b128 v[224:227], v161 offset:36864
	ds_read_b128 v[228:231], v161 offset:37888
	ds_read_b128 v[232:235], v161 offset:38912
	ds_read_b128 v[236:239], v161 offset:39936
	global_load_lds_dwordx4 v[246:247], off
	v_lshl_add_u64 v[246:247], s[58:59], 0, v[146:147]
	s_mov_b32 m0, s57
	s_nop 0
	global_load_lds_dwordx4 v[246:247], off
	s_waitcnt vmcnt(8)
	s_waitcnt lgkmcnt(0)
	s_setprio 1
	s_barrier
	v_mfma_f32_16x16x32_bf16 v[126:129], v[156:159], v[208:211], v[126:129]
	v_mfma_f32_16x16x32_bf16 v[122:125], v[166:169], v[208:211], v[122:125]
	v_mfma_f32_16x16x32_bf16 v[110:113], v[156:159], v[216:219], v[110:113]
	v_mfma_f32_16x16x32_bf16 v[106:109], v[166:169], v[216:219], v[106:109]
	v_mfma_f32_16x16x32_bf16 v[94:97], v[156:159], v[224:227], v[94:97]
	v_mfma_f32_16x16x32_bf16 v[90:93], v[166:169], v[224:227], v[90:93]
	v_mfma_f32_16x16x32_bf16 v[78:81], v[156:159], v[232:235], v[78:81]
	v_mfma_f32_16x16x32_bf16 v[74:77], v[166:169], v[232:235], v[74:77]
	s_setprio 0
	s_setprio 1
	v_mfma_f32_16x16x32_bf16 v[126:129], v[162:165], v[212:215], v[126:129]
	v_mfma_f32_16x16x32_bf16 v[122:125], v[170:173], v[212:215], v[122:125]
	v_mfma_f32_16x16x32_bf16 v[110:113], v[162:165], v[220:223], v[110:113]
	v_mfma_f32_16x16x32_bf16 v[106:109], v[170:173], v[220:223], v[106:109]
	v_mfma_f32_16x16x32_bf16 v[94:97], v[162:165], v[228:231], v[94:97]
	v_mfma_f32_16x16x32_bf16 v[90:93], v[170:173], v[228:231], v[90:93]
	v_mfma_f32_16x16x32_bf16 v[78:81], v[162:165], v[236:239], v[78:81]
	v_mfma_f32_16x16x32_bf16 v[74:77], v[170:173], v[236:239], v[74:77]
	s_setprio 0
	s_setprio 1
	v_mfma_f32_16x16x32_bf16 v[118:121], v[174:177], v[208:211], v[118:121]
	v_mfma_f32_16x16x32_bf16 v[114:117], v[182:185], v[208:211], v[114:117]
	v_mfma_f32_16x16x32_bf16 v[102:105], v[174:177], v[216:219], v[102:105]
	v_mfma_f32_16x16x32_bf16 v[98:101], v[182:185], v[216:219], v[98:101]
	v_mfma_f32_16x16x32_bf16 v[86:89], v[174:177], v[224:227], v[86:89]
	v_mfma_f32_16x16x32_bf16 v[82:85], v[182:185], v[224:227], v[82:85]
	v_mfma_f32_16x16x32_bf16 v[70:73], v[174:177], v[232:235], v[70:73]
	v_mfma_f32_16x16x32_bf16 v[66:69], v[182:185], v[232:235], v[66:69]
	s_setprio 0
	s_setprio 1
	v_mfma_f32_16x16x32_bf16 v[118:121], v[178:181], v[212:215], v[118:121]
	v_mfma_f32_16x16x32_bf16 v[114:117], v[204:207], v[212:215], v[114:117]
	v_mfma_f32_16x16x32_bf16 v[102:105], v[178:181], v[220:223], v[102:105]
	v_mfma_f32_16x16x32_bf16 v[98:101], v[204:207], v[220:223], v[98:101]
	v_mfma_f32_16x16x32_bf16 v[86:89], v[178:181], v[228:231], v[86:89]
	v_mfma_f32_16x16x32_bf16 v[82:85], v[204:207], v[228:231], v[82:85]
	v_mfma_f32_16x16x32_bf16 v[70:73], v[178:181], v[236:239], v[70:73]
	v_mfma_f32_16x16x32_bf16 v[66:69], v[204:207], v[236:239], v[66:69]
	s_setprio 0
	s_barrier
; #define PG8_STAGE(bufoff, gbase, voff) do { _Pragma("unroll") for (int _i = 0; _i < 2; ++_i) \
;         __builtin_amdgcn_global_load_lds((const unsigned*)((const char*)(gbase) + (voff)[_i]), (PG8_LAS unsigned*)(lds + (bufoff) + ldsw + _i * 8192), 16, 0, 0); } while (0)
; #define PG8_LDA(dst, b, h) do { _Pragma("unroll") for (int m = 0; m < 4; ++m) _Pragma("unroll") for (int k = 0; k < 2; ++k) dst[m][k] = *(const PG8_LAS bf16x8*)(lds + PG8_SA(b, h) + aoff + m * 2048 + k * 1024); } while (0)
; #define PG8_MMA(ai, bj, At, Bt) do { __builtin_amdgcn_s_setprio(1); _Pragma("unroll") for (int m = 0; m < 4; ++m) _Pragma("unroll") for (int n = 0; n < 2; ++n) _Pragma("unroll") for (int k = 0; k < 2; ++k) \
;         acc[ai][bj][m][n] = __builtin_amdgcn_mfma_f32_16x16x32_bf16(Bt[n][k], At[m][k], acc[ai][bj][m][n], 0, 0, 0); __builtin_amdgcn_s_setprio(0); } while (0)
; #define PG8_WAIT_V(n) asm volatile("s_waitcnt vmcnt(" #n ")" ::: "memory")
; #define PG8_WAIT_L(n) asm volatile("s_waitcnt lgkmcnt(" #n ")" ::: "memory")
; #define PG8_BAR __builtin_amdgcn_s_barrier()
; #define PG8_SCHED __builtin_amdgcn_sched_barrier(0)
;     __device__ __forceinline__ void operator()(const f32x4 (&acc)[2][2][4][2], const Unit& u, int wr, int wc, int fr, int fq) const {
;     ...
;             for (int m = 0; m < 4; ++m) { const size_t row = (size_t)(row0 + ai * HALF + m * 16); float ss = 0.f;
; #pragma unroll
;                 for (int bj = 0; bj < 2; ++bj) { const size_t off = row * DM + col0 + bj * HALF;
;                     f32x4 v0 = acc[ai][bj][m][0] + *(const f32x4*)(base + off), v1 = acc[ai][bj][m][1] + *(const f32x4*)(base + off + 4);
; template <class Epi, class Sched, bool ALIGN_EPI = false, bool SP2 = false>
; __device__ __forceinline__ void gemm_phase(PG8_LAS unsigned char* lds, const Gemm g, const Sched& S, const Epi& E) {
;     ...
;             PG8_LDA(At, 1, 1); PG8_STAGE(PG8_SB(1, 0), b3, voffB); PG8_STAGE(PG8_SB(1, 1), b3 + hstep, voffB); PG8_STAGE(PG8_SA(1, 0), a3, voffA);
;             PG8_WAIT_V(8); PG8_WAIT_L(0); PG8_BAR; PG8_MMA(1, 0, At, B0); PG8_MMA(1, 1, At, B1); PG8_BAR; PG8_SCHED;
	s_add_i32 s47, s47, s4
	v_lshl_add_u64 v[186:187], v[186:187], 0, s[68:69]
	s_mov_b32 m0, s47
	ds_read_b128 v[208:211], v161 offset:49152
	ds_read_b128 v[212:215], v161 offset:50176
	ds_read_b128 v[216:219], v161 offset:51200
	ds_read_b128 v[220:223], v161 offset:52224
	ds_read_b128 v[224:227], v161 offset:53248
	ds_read_b128 v[228:231], v161 offset:54272
	ds_read_b128 v[232:235], v161 offset:55296
	ds_read_b128 v[236:239], v161 offset:56320
	global_load_lds_dwordx4 v[186:187], off
	s_add_i32 m0, s47, 0x2000
	s_add_u32 s40, s40, 0x80080
	v_lshl_add_u64 v[186:187], v[240:241], 0, s[68:69]
	s_addc_u32 s41, s41, 0
	s_add_i32 s47, s76, s4
	global_load_lds_dwordx4 v[186:187], off
	v_lshl_add_u64 v[186:187], s[40:41], 0, v[148:149]
	s_mov_b32 m0, s47
	s_nop 0
	global_load_lds_dwordx4 v[186:187], off
	v_lshl_add_u64 v[186:187], s[40:41], 0, v[144:145]
	s_add_i32 m0, s47, 0x2000
	s_nop 0
	global_load_lds_dwordx4 v[186:187], off
	v_lshl_add_u64 v[186:187], v[242:243], 0, s[68:69]
	s_mov_b32 m0, s67
	s_nop 0
	global_load_lds_dwordx4 v[186:187], off
	v_lshl_add_u64 v[186:187], v[244:245], 0, s[68:69]
	s_mov_b32 m0, s28
	s_nop 0
	global_load_lds_dwordx4 v[186:187], off
	s_nop 0
	s_waitcnt vmcnt(8)
	s_waitcnt lgkmcnt(0)
	s_setprio 1
	s_barrier
	v_mfma_f32_16x16x32_bf16 v[62:65], v[156:159], v[208:211], v[62:65]
	v_mfma_f32_16x16x32_bf16 v[58:61], v[166:169], v[208:211], v[58:61]
	v_mfma_f32_16x16x32_bf16 v[46:49], v[156:159], v[216:219], v[46:49]
	v_mfma_f32_16x16x32_bf16 v[42:45], v[166:169], v[216:219], v[42:45]
	v_mfma_f32_16x16x32_bf16 v[30:33], v[156:159], v[224:227], v[30:33]
	v_mfma_f32_16x16x32_bf16 v[26:29], v[166:169], v[224:227], v[26:29]
	v_mfma_f32_16x16x32_bf16 v[14:17], v[156:159], v[232:235], v[14:17]
	v_mfma_f32_16x16x32_bf16 v[10:13], v[166:169], v[232:235], v[10:13]
	v_mfma_f32_16x16x32_bf16 v[62:65], v[162:165], v[212:215], v[62:65]
	v_mfma_f32_16x16x32_bf16 v[58:61], v[170:173], v[212:215], v[58:61]
	v_mfma_f32_16x16x32_bf16 v[46:49], v[162:165], v[220:223], v[46:49]
	v_mfma_f32_16x16x32_bf16 v[42:45], v[170:173], v[220:223], v[42:45]
	v_mfma_f32_16x16x32_bf16 v[30:33], v[162:165], v[228:231], v[30:33]
	v_mfma_f32_16x16x32_bf16 v[26:29], v[170:173], v[228:231], v[26:29]
	v_mfma_f32_16x16x32_bf16 v[14:17], v[162:165], v[236:239], v[14:17]
	v_mfma_f32_16x16x32_bf16 v[10:13], v[170:173], v[236:239], v[10:13]
	v_mfma_f32_16x16x32_bf16 v[54:57], v[174:177], v[208:211], v[54:57]
	v_mfma_f32_16x16x32_bf16 v[50:53], v[182:185], v[208:211], v[50:53]
	v_mfma_f32_16x16x32_bf16 v[38:41], v[174:177], v[216:219], v[38:41]
	v_mfma_f32_16x16x32_bf16 v[34:37], v[182:185], v[216:219], v[34:37]
	v_mfma_f32_16x16x32_bf16 v[22:25], v[174:177], v[224:227], v[22:25]
	v_mfma_f32_16x16x32_bf16 v[18:21], v[182:185], v[224:227], v[18:21]
	v_mfma_f32_16x16x32_bf16 v[6:9], v[174:177], v[232:235], v[6:9]
	v_mfma_f32_16x16x32_bf16 v[2:5], v[182:185], v[232:235], v[2:5]
	v_mfma_f32_16x16x32_bf16 v[54:57], v[178:181], v[212:215], v[54:57]
	v_mfma_f32_16x16x32_bf16 v[50:53], v[204:207], v[212:215], v[50:53]
	v_mfma_f32_16x16x32_bf16 v[38:41], v[178:181], v[220:223], v[38:41]
	v_mfma_f32_16x16x32_bf16 v[34:37], v[204:207], v[220:223], v[34:37]
	v_mfma_f32_16x16x32_bf16 v[22:25], v[178:181], v[228:231], v[22:25]
	v_mfma_f32_16x16x32_bf16 v[18:21], v[204:207], v[228:231], v[18:21]
	v_mfma_f32_16x16x32_bf16 v[6:9], v[178:181], v[236:239], v[6:9]
	v_mfma_f32_16x16x32_bf16 v[2:5], v[204:207], v[236:239], v[2:5]
	s_setprio 0
	s_barrier
	s_add_i32 s46, s46, 2
	s_add_u32 vcc_lo, vcc_lo, 0x100
	s_addc_u32 vcc_hi, vcc_hi, 0
	s_add_u32 s78, s78, 0x100
	s_addc_u32 s79, s79, 0
	s_cmp_gt_u32 s46, 29
	s_cbranch_scc0 .LBB0_98
	v_lshl_add_u32 v156, s73, 8, v1
	v_lshl_or_b32 v157, s54, 8, v160
	v_lshl_add_u32 v157, v156, 11, v157
	v_mov_b32_e32 v247, 0
	v_lshlrev_b32_e32 v246, 2, v157
	v_lshl_add_u64 v[162:163], s[8:9], 0, v[246:247]
	v_lshlrev_b32_e32 v246, 1, v157
	v_lshl_add_u64 v[244:245], s[70:71], 0, v[246:247]
	s_mov_b32 s41, 0
	global_load_dwordx4 v[164:167], v[162:163], off
	global_load_dwordx4 v[168:171], v[162:163], off offset:16
	global_load_dwordx4 v[172:175], v[162:163], off offset:512
	global_load_dwordx4 v[176:179], v[162:163], off offset:528
	s_mov_b32 s40, 0x20000
	v_lshl_add_u64 v[246:247], v[162:163], 0, s[40:41]
	global_load_dwordx4 v[180:183], v[246:247], off
	global_load_dwordx4 v[184:187], v[246:247], off offset:16
	global_load_dwordx4 v[204:207], v[246:247], off offset:512
	global_load_dwordx4 v[208:211], v[246:247], off offset:528
	s_mov_b32 s40, 0x40000
	v_lshl_add_u64 v[246:247], v[162:163], 0, s[40:41]
	global_load_dwordx4 v[212:215], v[246:247], off
	global_load_dwordx4 v[216:219], v[246:247], off offset:16
	global_load_dwordx4 v[220:223], v[246:247], off offset:512
	global_load_dwordx4 v[224:227], v[246:247], off offset:528
	s_mov_b32 s40, 0x60000
	v_lshl_add_u64 v[246:247], v[162:163], 0, s[40:41]
	global_load_dwordx4 v[228:231], v[246:247], off
	global_load_dwordx4 v[232:235], v[246:247], off offset:16
	global_load_dwordx4 v[236:239], v[246:247], off offset:512
	global_load_dwordx4 v[240:243], v[246:247], off offset:528
	s_and_b64 vcc, exec, s[36:37]
	s_cbranch_vccz .Lx1_nobar
	s_barrier

; #define PG8_STAGE(bufoff, gbase, voff) do { _Pragma("unroll") for (int _i = 0; _i < 2; ++_i) \
;         __builtin_amdgcn_global_load_lds((const unsigned*)((const char*)(gbase) + (voff)[_i]), (PG8_LAS unsigned*)(lds + (bufoff) + ldsw + _i * 8192), 16, 0, 0); } while (0)
; #define PG8_LDA(dst, b, h) do { _Pragma("unroll") for (int m = 0; m < 4; ++m) _Pragma("unroll") for (int k = 0; k < 2; ++k) dst[m][k] = *(const PG8_LAS bf16x8*)(lds + PG8_SA(b, h) + aoff + m * 2048 + k * 1024); } while (0)
; #define PG8_LDB(dst, b, h) do { _Pragma("unroll") for (int n = 0; n < 2; ++n) _Pragma("unroll") for (int k = 0; k < 2; ++k) dst[n][k] = *(const PG8_LAS bf16x8*)(lds + PG8_SB(b, h) + boff + n * 2048 + k * 1024); } while (0)
; #define PG8_MMA(ai, bj, At, Bt) do { __builtin_amdgcn_s_setprio(1); _Pragma("unroll") for (int m = 0; m < 4; ++m) _Pragma("unroll") for (int n = 0; n < 2; ++n) _Pragma("unroll") for (int k = 0; k < 2; ++k) \
;         acc[ai][bj][m][n] = __builtin_amdgcn_mfma_f32_16x16x32_bf16(Bt[n][k], At[m][k], acc[ai][bj][m][n], 0, 0, 0); __builtin_amdgcn_s_setprio(0); } while (0)
; #define PG8_WAIT_V(n) asm volatile("s_waitcnt vmcnt(" #n ")" ::: "memory")
; #define PG8_WAIT_L(n) asm volatile("s_waitcnt lgkmcnt(" #n ")" ::: "memory")
; template <class Epi, class Sched, bool ALIGN_EPI = false, bool SP2 = false>
; __device__ __forceinline__ void gemm_phase(PG8_LAS unsigned char* lds, const Gemm g, const Sched& S, const Epi& E) {
;     ...
;             const bool last = (t == nt - 2);
;             const char* a1 = cA + (size_t)(t + 1) * kstep;
;             const char* a2 = last ? nA : cA + (size_t)(t + 2) * kstep; const char* b2 = last ? nB : cB + (size_t)(t + 2) * kstep;
;             const char* a3 = a2 + kstep; const char* b3 = b2 + kstep;
;             if (last && has_next) S.a_ready(nxt);
;             if constexpr (SP2) {
;             PG8_LDB(B0, 0, 0); PG8_LDB(B1, 0, 1); PG8_SCHED; PG8_LDA(At, 0, 0); PG8_STAGE(PG8_SA(1, 1), a1 + hstep, voffA);
;             PG8_WAIT_V(8); PG8_WAIT_L(0); PG8_BAR; PG8_MMA(0, 0, At, B0); PG8_MMA(0, 1, At, B1); PG8_BAR; PG8_SCHED;
;             PG8_LDA(At, 0, 1); PG8_STAGE(PG8_SB(0, 0), b2, voffB); PG8_STAGE(PG8_SB(0, 1), b2 + hstep, voffB); PG8_STAGE(PG8_SA(0, 0), a2, voffA);
;             PG8_WAIT_V(8); PG8_WAIT_L(0); PG8_BAR; PG8_MMA(1, 0, At, B0); PG8_MMA(1, 1, At, B1); PG8_BAR; PG8_SCHED;
.LBB0_136:
	s_add_u32 s18, s58, 0xfffe0080
	s_addc_u32 s19, s59, -1
	s_add_i32 s46, 0, 0x10000
	s_cmp_eq_u32 s79, 4
	s_cselect_b32 s63, s37, s19
	s_cselect_b32 s62, s73, s18
	s_cselect_b32 s19, s11, s78
	s_cselect_b32 s18, s84, s85
	s_add_i32 s76, 0, 0x14000
	v_add_u32_e32 v172, s46, v1
	v_add_u32_e32 v203, s76, v1
	ds_read_b128 v[160:163], v172
	ds_read_b128 v[164:167], v172 offset:1024
	ds_read_b128 v[168:171], v172 offset:2048
	ds_read_b128 v[172:175], v172 offset:3072
	ds_read_b128 v[176:179], v203
	ds_read_b128 v[180:183], v203 offset:1024
	ds_read_b128 v[184:187], v203 offset:2048
	ds_read_b128 v[204:207], v203 offset:3072
	v_lshl_add_u64 v[240:241], s[58:59], 0, v[156:157]
	s_add_i32 m0, s5, 0xc000
	ds_read_b128 v[208:211], v143
	ds_read_b128 v[212:215], v143 offset:1024
	ds_read_b128 v[216:219], v143 offset:2048
	ds_read_b128 v[220:223], v143 offset:3072
	ds_read_b128 v[224:227], v143 offset:4096
	ds_read_b128 v[228:231], v143 offset:5120
	ds_read_b128 v[232:235], v143 offset:6144
	ds_read_b128 v[236:239], v143 offset:7168
	global_load_lds_dwordx4 v[240:241], off
	v_lshl_add_u64 v[240:241], s[58:59], 0, v[158:159]
	s_add_i32 m0, s5, 0xe000
	s_nop 0
	global_load_lds_dwordx4 v[240:241], off
	s_nop 0
	s_waitcnt vmcnt(8)
	s_waitcnt lgkmcnt(0)
	s_setprio 1
	s_barrier
	v_mfma_f32_16x16x32_bf16 v[126:129], v[160:163], v[208:211], v[126:129]
	v_mfma_f32_16x16x32_bf16 v[122:125], v[168:171], v[208:211], v[122:125]
	v_mfma_f32_16x16x32_bf16 v[110:113], v[160:163], v[216:219], v[110:113]
	v_mfma_f32_16x16x32_bf16 v[106:109], v[168:171], v[216:219], v[106:109]
	v_mfma_f32_16x16x32_bf16 v[94:97], v[160:163], v[224:227], v[94:97]
	v_mfma_f32_16x16x32_bf16 v[90:93], v[168:171], v[224:227], v[90:93]
	v_mfma_f32_16x16x32_bf16 v[78:81], v[160:163], v[232:235], v[78:81]
	v_mfma_f32_16x16x32_bf16 v[74:77], v[168:171], v[232:235], v[74:77]
	s_setprio 0
	s_setprio 1
	v_mfma_f32_16x16x32_bf16 v[126:129], v[164:167], v[212:215], v[126:129]
	v_mfma_f32_16x16x32_bf16 v[122:125], v[172:175], v[212:215], v[122:125]
	v_mfma_f32_16x16x32_bf16 v[110:113], v[164:167], v[220:223], v[110:113]
	v_mfma_f32_16x16x32_bf16 v[106:109], v[172:175], v[220:223], v[106:109]
	v_mfma_f32_16x16x32_bf16 v[94:97], v[164:167], v[228:231], v[94:97]
	v_mfma_f32_16x16x32_bf16 v[90:93], v[172:175], v[228:231], v[90:93]
	v_mfma_f32_16x16x32_bf16 v[78:81], v[164:167], v[236:239], v[78:81]
	v_mfma_f32_16x16x32_bf16 v[74:77], v[172:175], v[236:239], v[74:77]
	s_setprio 0
	s_setprio 1
	v_mfma_f32_16x16x32_bf16 v[118:121], v[176:179], v[208:211], v[118:121]
	v_mfma_f32_16x16x32_bf16 v[114:117], v[184:187], v[208:211], v[114:117]
	v_mfma_f32_16x16x32_bf16 v[102:105], v[176:179], v[216:219], v[102:105]
	v_mfma_f32_16x16x32_bf16 v[98:101], v[184:187], v[216:219], v[98:101]
	v_mfma_f32_16x16x32_bf16 v[86:89], v[176:179], v[224:227], v[86:89]
	v_mfma_f32_16x16x32_bf16 v[82:85], v[184:187], v[224:227], v[82:85]
	v_mfma_f32_16x16x32_bf16 v[70:73], v[176:179], v[232:235], v[70:73]
	v_mfma_f32_16x16x32_bf16 v[66:69], v[184:187], v[232:235], v[66:69]
	s_setprio 0
	s_setprio 1
	v_mfma_f32_16x16x32_bf16 v[118:121], v[180:183], v[212:215], v[118:121]
	v_mfma_f32_16x16x32_bf16 v[114:117], v[204:207], v[212:215], v[114:117]
	v_mfma_f32_16x16x32_bf16 v[102:105], v[180:183], v[220:223], v[102:105]
	v_mfma_f32_16x16x32_bf16 v[98:101], v[204:207], v[220:223], v[98:101]
	v_mfma_f32_16x16x32_bf16 v[86:89], v[180:183], v[228:231], v[86:89]
	v_mfma_f32_16x16x32_bf16 v[82:85], v[204:207], v[228:231], v[82:85]
	v_mfma_f32_16x16x32_bf16 v[70:73], v[180:183], v[236:239], v[70:73]
	v_mfma_f32_16x16x32_bf16 v[66:69], v[204:207], v[236:239], v[66:69]
	s_setprio 0
	s_barrier
	s_add_i32 s46, s46, s4
	v_lshl_add_u64 v[240:241], s[18:19], 0, v[148:149]
	s_mov_b32 m0, s46
	ds_read_b128 v[208:211], v143 offset:16384
	ds_read_b128 v[212:215], v143 offset:17408
	ds_read_b128 v[216:219], v143 offset:18432
	ds_read_b128 v[220:223], v143 offset:19456
	ds_read_b128 v[224:227], v143 offset:20480
	ds_read_b128 v[228:231], v143 offset:21504
	ds_read_b128 v[232:235], v143 offset:22528
	ds_read_b128 v[236:239], v143 offset:23552
	global_load_lds_dwordx4 v[240:241], off
	s_add_i32 m0, s46, 0x2000
	s_add_u32 s46, s18, 0x20000
	v_lshl_add_u64 v[242:243], s[18:19], 0, v[144:145]
	s_addc_u32 s47, s19, 0
	s_add_i32 s76, s76, s4
	global_load_lds_dwordx4 v[242:243], off
	v_lshl_add_u64 v[244:245], s[46:47], 0, v[148:149]
	s_mov_b32 m0, s76
	v_lshl_add_u64 v[246:247], s[62:63], 0, v[146:147]
	global_load_lds_dwordx4 v[244:245], off
	v_lshl_add_u64 v[244:245], s[46:47], 0, v[144:145]
	s_add_i32 m0, s76, 0x2000
	s_nop 0
	global_load_lds_dwordx4 v[244:245], off
	v_lshl_add_u64 v[244:245], s[62:63], 0, v[150:151]
	s_mov_b32 m0, s5
	s_nop 0
	global_load_lds_dwordx4 v[244:245], off
	s_mov_b32 m0, s28
	s_nop 0
	global_load_lds_dwordx4 v[246:247], off
	s_waitcnt vmcnt(8)
	s_waitcnt lgkmcnt(0)
	s_setprio 1
	s_barrier
; #define PG8_STAGE(bufoff, gbase, voff) do { _Pragma("unroll") for (int _i = 0; _i < 2; ++_i) \
;         __builtin_amdgcn_global_load_lds((const unsigned*)((const char*)(gbase) + (voff)[_i]), (PG8_LAS unsigned*)(lds + (bufoff) + ldsw + _i * 8192), 16, 0, 0); } while (0)
; #define PG8_LDA(dst, b, h) do { _Pragma("unroll") for (int m = 0; m < 4; ++m) _Pragma("unroll") for (int k = 0; k < 2; ++k) dst[m][k] = *(const PG8_LAS bf16x8*)(lds + PG8_SA(b, h) + aoff + m * 2048 + k * 1024); } while (0)
; #define PG8_LDB(dst, b, h) do { _Pragma("unroll") for (int n = 0; n < 2; ++n) _Pragma("unroll") for (int k = 0; k < 2; ++k) dst[n][k] = *(const PG8_LAS bf16x8*)(lds + PG8_SB(b, h) + boff + n * 2048 + k * 1024); } while (0)
; #define PG8_MMA(ai, bj, At, Bt) do { __builtin_amdgcn_s_setprio(1); _Pragma("unroll") for (int m = 0; m < 4; ++m) _Pragma("unroll") for (int n = 0; n < 2; ++n) _Pragma("unroll") for (int k = 0; k < 2; ++k) \
;         acc[ai][bj][m][n] = __builtin_amdgcn_mfma_f32_16x16x32_bf16(Bt[n][k], At[m][k], acc[ai][bj][m][n], 0, 0, 0); __builtin_amdgcn_s_setprio(0); } while (0)
; #define PG8_WAIT_V(n) asm volatile("s_waitcnt vmcnt(" #n ")" ::: "memory")
; #define PG8_WAIT_L(n) asm volatile("s_waitcnt lgkmcnt(" #n ")" ::: "memory")
; #define PG8_BAR __builtin_amdgcn_s_barrier()
; #define PG8_SCHED __builtin_amdgcn_sched_barrier(0)
; template <class Epi, class Sched, bool ALIGN_EPI = false, bool SP2 = false>
; __device__ __forceinline__ void gemm_phase(PG8_LAS unsigned char* lds, const Gemm g, const Sched& S, const Epi& E) {
;     ...
;             PG8_WAIT_V(8); PG8_WAIT_L(0); PG8_BAR; PG8_MMA(1, 0, At, B0); PG8_MMA(1, 1, At, B1); PG8_BAR; PG8_SCHED;
;             PG8_LDB(B0, 1, 0); PG8_LDB(B1, 1, 1); PG8_SCHED; PG8_LDA(At, 1, 0); PG8_STAGE(PG8_SA(0, 1), a2 + hstep, voffA);
;             PG8_WAIT_V(8); PG8_WAIT_L(0); PG8_BAR; PG8_MMA(0, 0, At, B0); PG8_MMA(0, 1, At, B1); PG8_BAR; PG8_SCHED;
	v_mfma_f32_16x16x32_bf16 v[62:65], v[160:163], v[208:211], v[62:65]
	v_mfma_f32_16x16x32_bf16 v[58:61], v[168:171], v[208:211], v[58:61]
	v_mfma_f32_16x16x32_bf16 v[46:49], v[160:163], v[216:219], v[46:49]
	v_mfma_f32_16x16x32_bf16 v[42:45], v[168:171], v[216:219], v[42:45]
	v_mfma_f32_16x16x32_bf16 v[30:33], v[160:163], v[224:227], v[30:33]
	v_mfma_f32_16x16x32_bf16 v[26:29], v[168:171], v[224:227], v[26:29]
	v_mfma_f32_16x16x32_bf16 v[14:17], v[160:163], v[232:235], v[14:17]
	v_mfma_f32_16x16x32_bf16 v[10:13], v[168:171], v[232:235], v[10:13]
	v_mfma_f32_16x16x32_bf16 v[62:65], v[164:167], v[212:215], v[62:65]
	v_mfma_f32_16x16x32_bf16 v[58:61], v[172:175], v[212:215], v[58:61]
	v_mfma_f32_16x16x32_bf16 v[46:49], v[164:167], v[220:223], v[46:49]
	v_mfma_f32_16x16x32_bf16 v[42:45], v[172:175], v[220:223], v[42:45]
	v_mfma_f32_16x16x32_bf16 v[30:33], v[164:167], v[228:231], v[30:33]
	v_mfma_f32_16x16x32_bf16 v[26:29], v[172:175], v[228:231], v[26:29]
	v_mfma_f32_16x16x32_bf16 v[14:17], v[164:167], v[236:239], v[14:17]
	v_mfma_f32_16x16x32_bf16 v[10:13], v[172:175], v[236:239], v[10:13]
	v_mfma_f32_16x16x32_bf16 v[54:57], v[176:179], v[208:211], v[54:57]
	v_mfma_f32_16x16x32_bf16 v[50:53], v[184:187], v[208:211], v[50:53]
	v_mfma_f32_16x16x32_bf16 v[38:41], v[176:179], v[216:219], v[38:41]
	v_mfma_f32_16x16x32_bf16 v[34:37], v[184:187], v[216:219], v[34:37]
	v_mfma_f32_16x16x32_bf16 v[22:25], v[176:179], v[224:227], v[22:25]
	v_mfma_f32_16x16x32_bf16 v[18:21], v[184:187], v[224:227], v[18:21]
	v_mfma_f32_16x16x32_bf16 v[6:9], v[176:179], v[232:235], v[6:9]
	v_mfma_f32_16x16x32_bf16 v[2:5], v[184:187], v[232:235], v[2:5]
	v_mfma_f32_16x16x32_bf16 v[54:57], v[180:183], v[212:215], v[54:57]
	v_mfma_f32_16x16x32_bf16 v[50:53], v[204:207], v[212:215], v[50:53]
	v_mfma_f32_16x16x32_bf16 v[38:41], v[180:183], v[220:223], v[38:41]
	v_mfma_f32_16x16x32_bf16 v[34:37], v[204:207], v[220:223], v[34:37]
	v_mfma_f32_16x16x32_bf16 v[22:25], v[180:183], v[228:231], v[22:25]
	v_mfma_f32_16x16x32_bf16 v[18:21], v[204:207], v[228:231], v[18:21]
	v_mfma_f32_16x16x32_bf16 v[6:9], v[180:183], v[236:239], v[6:9]
	v_mfma_f32_16x16x32_bf16 v[2:5], v[204:207], v[236:239], v[2:5]
	s_setprio 0
	s_barrier
	s_add_i32 s76, 0, 0x18000
	s_add_i32 s77, 0, 0x1c000
	v_add_u32_e32 v172, s76, v1
	v_add_u32_e32 v203, s77, v1
	ds_read_b128 v[160:163], v172
	ds_read_b128 v[164:167], v172 offset:1024
	ds_read_b128 v[168:171], v172 offset:2048
	ds_read_b128 v[172:175], v172 offset:3072
	ds_read_b128 v[176:179], v203
	ds_read_b128 v[180:183], v203 offset:1024
	ds_read_b128 v[184:187], v203 offset:2048
	ds_read_b128 v[204:207], v203 offset:3072
	s_add_u32 s46, s62, 0x20000
	s_addc_u32 s47, s63, 0
	s_mov_b32 m0, s30
	v_lshl_add_u64 v[248:249], s[46:47], 0, v[150:151]
	ds_read_b128 v[208:211], v143 offset:32768
	ds_read_b128 v[212:215], v143 offset:33792
	ds_read_b128 v[216:219], v143 offset:34816
	ds_read_b128 v[220:223], v143 offset:35840
	ds_read_b128 v[224:227], v143 offset:36864
	ds_read_b128 v[228:231], v143 offset:37888
	ds_read_b128 v[232:235], v143 offset:38912
	ds_read_b128 v[236:239], v143 offset:39936
	global_load_lds_dwordx4 v[248:249], off
	v_lshl_add_u64 v[248:249], s[46:47], 0, v[146:147]
	s_mov_b32 m0, s34
	s_nop 0
	global_load_lds_dwordx4 v[248:249], off
	s_waitcnt vmcnt(8)
	s_waitcnt lgkmcnt(0)
	s_setprio 1
	s_barrier
	v_mfma_f32_16x16x32_bf16 v[126:129], v[160:163], v[208:211], v[126:129]
	v_mfma_f32_16x16x32_bf16 v[122:125], v[168:171], v[208:211], v[122:125]
	v_mfma_f32_16x16x32_bf16 v[110:113], v[160:163], v[216:219], v[110:113]
	v_mfma_f32_16x16x32_bf16 v[106:109], v[168:171], v[216:219], v[106:109]
	v_mfma_f32_16x16x32_bf16 v[94:97], v[160:163], v[224:227], v[94:97]
	v_mfma_f32_16x16x32_bf16 v[90:93], v[168:171], v[224:227], v[90:93]
	v_mfma_f32_16x16x32_bf16 v[78:81], v[160:163], v[232:235], v[78:81]
	v_mfma_f32_16x16x32_bf16 v[74:77], v[168:171], v[232:235], v[74:77]
	s_setprio 0
	s_setprio 1
	v_mfma_f32_16x16x32_bf16 v[126:129], v[164:167], v[212:215], v[126:129]
	v_mfma_f32_16x16x32_bf16 v[122:125], v[172:175], v[212:215], v[122:125]
	v_mfma_f32_16x16x32_bf16 v[110:113], v[164:167], v[220:223], v[110:113]
	v_mfma_f32_16x16x32_bf16 v[106:109], v[172:175], v[220:223], v[106:109]
	v_mfma_f32_16x16x32_bf16 v[94:97], v[164:167], v[228:231], v[94:97]
	v_mfma_f32_16x16x32_bf16 v[90:93], v[172:175], v[228:231], v[90:93]
	v_mfma_f32_16x16x32_bf16 v[78:81], v[164:167], v[236:239], v[78:81]
	v_mfma_f32_16x16x32_bf16 v[74:77], v[172:175], v[236:239], v[74:77]
	s_setprio 0
	s_setprio 1
	v_mfma_f32_16x16x32_bf16 v[118:121], v[176:179], v[208:211], v[118:121]
	v_mfma_f32_16x16x32_bf16 v[114:117], v[184:187], v[208:211], v[114:117]
	v_mfma_f32_16x16x32_bf16 v[102:105], v[176:179], v[216:219], v[102:105]
	v_mfma_f32_16x16x32_bf16 v[98:101], v[184:187], v[216:219], v[98:101]
	v_mfma_f32_16x16x32_bf16 v[86:89], v[176:179], v[224:227], v[86:89]
	v_mfma_f32_16x16x32_bf16 v[82:85], v[184:187], v[224:227], v[82:85]
	v_mfma_f32_16x16x32_bf16 v[70:73], v[176:179], v[232:235], v[70:73]
	v_mfma_f32_16x16x32_bf16 v[66:69], v[184:187], v[232:235], v[66:69]
	s_setprio 0
	s_setprio 1
	v_mfma_f32_16x16x32_bf16 v[118:121], v[180:183], v[212:215], v[118:121]
	v_mfma_f32_16x16x32_bf16 v[114:117], v[204:207], v[212:215], v[114:117]
	v_mfma_f32_16x16x32_bf16 v[102:105], v[180:183], v[220:223], v[102:105]
	v_mfma_f32_16x16x32_bf16 v[98:101], v[204:207], v[220:223], v[98:101]
	v_mfma_f32_16x16x32_bf16 v[86:89], v[180:183], v[228:231], v[86:89]
	v_mfma_f32_16x16x32_bf16 v[82:85], v[204:207], v[228:231], v[82:85]
	v_mfma_f32_16x16x32_bf16 v[70:73], v[180:183], v[236:239], v[70:73]
	v_mfma_f32_16x16x32_bf16 v[66:69], v[204:207], v[236:239], v[66:69]
	s_setprio 0
	s_barrier
; #define PG8_STAGE(bufoff, gbase, voff) do { _Pragma("unroll") for (int _i = 0; _i < 2; ++_i) \
;         __builtin_amdgcn_global_load_lds((const unsigned*)((const char*)(gbase) + (voff)[_i]), (PG8_LAS unsigned*)(lds + (bufoff) + ldsw + _i * 8192), 16, 0, 0); } while (0)
; #define PG8_LDA(dst, b, h) do { _Pragma("unroll") for (int m = 0; m < 4; ++m) _Pragma("unroll") for (int k = 0; k < 2; ++k) dst[m][k] = *(const PG8_LAS bf16x8*)(lds + PG8_SA(b, h) + aoff + m * 2048 + k * 1024); } while (0)
; #define PG8_MMA(ai, bj, At, Bt) do { __builtin_amdgcn_s_setprio(1); _Pragma("unroll") for (int m = 0; m < 4; ++m) _Pragma("unroll") for (int n = 0; n < 2; ++n) _Pragma("unroll") for (int k = 0; k < 2; ++k) \
;         acc[ai][bj][m][n] = __builtin_amdgcn_mfma_f32_16x16x32_bf16(Bt[n][k], At[m][k], acc[ai][bj][m][n], 0, 0, 0); __builtin_amdgcn_s_setprio(0); } while (0)
; #define PG8_WAIT_V(n) asm volatile("s_waitcnt vmcnt(" #n ")" ::: "memory")
; #define PG8_WAIT_L(n) asm volatile("s_waitcnt lgkmcnt(" #n ")" ::: "memory")
; #define PG8_BAR __builtin_amdgcn_s_barrier()
; #define PG8_SCHED __builtin_amdgcn_sched_barrier(0)
;     __device__ __forceinline__ void operator()(const f32x4 (&acc)[2][2][4][2], const Unit& u, int wr, int wc, int fr, int fq) const {
;         const int row0 = u.pm * BM + wr * 64 + fr, col0 = u.pn * BM + wc * 32 + 8 * fq;
;         const int tidn = (wr * 4 + wc) * 64 + fq * 16 + fr;
;         const u32x4* gp = (const u32x4*)G8 + (size_t)(u.pm * 16 + gsel + u.pn) * 8 * 512 + tidn;
;         u32x4* mp = M1 + (size_t)(u.pm * 8 + u.pn) * 16 * 512 + tidn;
;         constexpr float K255 = 1.0f / 255.0f;
; #pragma unroll
;         for (int ai = 0; ai < 2; ++ai)
; #pragma unroll
;             for (int m = 0; m < 4; ++m) { const size_t row = (size_t)(row0 + ai * HALF + m * 16);
;                 const u32x4 gw = gp[(ai * 4 + m) * 512];
; template <class Epi, class Sched, bool ALIGN_EPI = false, bool SP2 = false>
; __device__ __forceinline__ void gemm_phase(PG8_LAS unsigned char* lds, const Gemm g, const Sched& S, const Epi& E) {
;     ...
;             PG8_LDA(At, 1, 1); PG8_STAGE(PG8_SB(1, 0), b3, voffB); PG8_STAGE(PG8_SB(1, 1), b3 + hstep, voffB); PG8_STAGE(PG8_SA(1, 0), a3, voffA);
;             PG8_WAIT_V(8); PG8_WAIT_L(0); PG8_BAR; PG8_MMA(1, 0, At, B0); PG8_MMA(1, 1, At, B1); PG8_BAR; PG8_SCHED;
	s_add_i32 s46, s76, s4
	v_lshl_add_u64 v[240:241], v[240:241], 0, s[68:69]
	s_mov_b32 m0, s46
	ds_read_b128 v[208:211], v143 offset:49152
	ds_read_b128 v[212:215], v143 offset:50176
	ds_read_b128 v[216:219], v143 offset:51200
	ds_read_b128 v[220:223], v143 offset:52224
	ds_read_b128 v[224:227], v143 offset:53248
	ds_read_b128 v[228:231], v143 offset:54272
	ds_read_b128 v[232:235], v143 offset:55296
	ds_read_b128 v[236:239], v143 offset:56320
	global_load_lds_dwordx4 v[240:241], off
	s_add_i32 m0, s46, 0x2000
	s_add_u32 s18, s18, 0x20080
	v_lshl_add_u64 v[240:241], v[242:243], 0, s[68:69]
	s_addc_u32 s19, s19, 0
	s_add_i32 s46, s77, s4
	global_load_lds_dwordx4 v[240:241], off
	v_lshl_add_u64 v[240:241], s[18:19], 0, v[148:149]
	s_mov_b32 m0, s46
	s_nop 0
	global_load_lds_dwordx4 v[240:241], off
	v_lshl_add_u64 v[240:241], s[18:19], 0, v[144:145]
	s_add_i32 m0, s46, 0x2000
	s_nop 0
	global_load_lds_dwordx4 v[240:241], off
	v_lshl_add_u64 v[240:241], v[244:245], 0, s[68:69]
	s_mov_b32 m0, s54
	s_nop 0
	global_load_lds_dwordx4 v[240:241], off
	v_lshl_add_u64 v[240:241], v[246:247], 0, s[68:69]
	s_mov_b32 m0, s57
	s_nop 0
	global_load_lds_dwordx4 v[240:241], off
	s_nop 0
	s_waitcnt vmcnt(8)
	s_waitcnt lgkmcnt(0)
	s_setprio 1
	s_barrier
	v_mfma_f32_16x16x32_bf16 v[62:65], v[160:163], v[208:211], v[62:65]
	v_mfma_f32_16x16x32_bf16 v[58:61], v[168:171], v[208:211], v[58:61]
	v_mfma_f32_16x16x32_bf16 v[46:49], v[160:163], v[216:219], v[46:49]
	v_mfma_f32_16x16x32_bf16 v[42:45], v[168:171], v[216:219], v[42:45]
	v_mfma_f32_16x16x32_bf16 v[30:33], v[160:163], v[224:227], v[30:33]
	v_mfma_f32_16x16x32_bf16 v[26:29], v[168:171], v[224:227], v[26:29]
	v_mfma_f32_16x16x32_bf16 v[14:17], v[160:163], v[232:235], v[14:17]
	v_mfma_f32_16x16x32_bf16 v[10:13], v[168:171], v[232:235], v[10:13]
	v_mfma_f32_16x16x32_bf16 v[62:65], v[164:167], v[212:215], v[62:65]
	v_mfma_f32_16x16x32_bf16 v[58:61], v[172:175], v[212:215], v[58:61]
	v_mfma_f32_16x16x32_bf16 v[46:49], v[164:167], v[220:223], v[46:49]
	v_mfma_f32_16x16x32_bf16 v[42:45], v[172:175], v[220:223], v[42:45]
	v_mfma_f32_16x16x32_bf16 v[30:33], v[164:167], v[228:231], v[30:33]
	v_mfma_f32_16x16x32_bf16 v[26:29], v[172:175], v[228:231], v[26:29]
	v_mfma_f32_16x16x32_bf16 v[14:17], v[164:167], v[236:239], v[14:17]
	v_mfma_f32_16x16x32_bf16 v[10:13], v[172:175], v[236:239], v[10:13]
	v_mfma_f32_16x16x32_bf16 v[54:57], v[176:179], v[208:211], v[54:57]
	v_mfma_f32_16x16x32_bf16 v[50:53], v[184:187], v[208:211], v[50:53]
	v_mfma_f32_16x16x32_bf16 v[38:41], v[176:179], v[216:219], v[38:41]
	v_mfma_f32_16x16x32_bf16 v[34:37], v[184:187], v[216:219], v[34:37]
	v_mfma_f32_16x16x32_bf16 v[22:25], v[176:179], v[224:227], v[22:25]
	v_mfma_f32_16x16x32_bf16 v[18:21], v[184:187], v[224:227], v[18:21]
	v_mfma_f32_16x16x32_bf16 v[6:9], v[176:179], v[232:235], v[6:9]
	v_mfma_f32_16x16x32_bf16 v[2:5], v[184:187], v[232:235], v[2:5]
	v_mfma_f32_16x16x32_bf16 v[54:57], v[180:183], v[212:215], v[54:57]
	v_mfma_f32_16x16x32_bf16 v[50:53], v[204:207], v[212:215], v[50:53]
	v_mfma_f32_16x16x32_bf16 v[38:41], v[180:183], v[220:223], v[38:41]
	v_mfma_f32_16x16x32_bf16 v[34:37], v[204:207], v[220:223], v[34:37]
	v_mfma_f32_16x16x32_bf16 v[22:25], v[180:183], v[228:231], v[22:25]
	v_mfma_f32_16x16x32_bf16 v[18:21], v[204:207], v[228:231], v[18:21]
	v_mfma_f32_16x16x32_bf16 v[6:9], v[180:183], v[236:239], v[6:9]
	v_mfma_f32_16x16x32_bf16 v[2:5], v[204:207], v[236:239], v[2:5]
	s_setprio 0
	s_barrier
	s_add_i32 s79, s79, 2
	s_add_u32 s58, s58, 0x100
	s_addc_u32 s59, s59, 0
	s_add_u32 s85, s85, 0x100
	s_addc_u32 s78, s78, 0
	s_cmp_gt_u32 s79, 5
	s_cbranch_scc0 .LBB0_136
	s_lshl_b32 s11, s67, 4
	s_add_i32 s18, s11, s86
	s_ashr_i32 s19, s18, 31
	s_lshl_b64 s[46:47], s[18:19], 16
	v_lshl_add_u64 v[162:163], v[152:153], 0, s[46:47]
	s_lshl_b32 s11, s67, 3
	s_sub_i32 s18, s18, s11
	s_ashr_i32 s19, s18, 31
	s_lshl_b64 s[18:19], s[18:19], 17
	v_lshl_add_u64 v[160:161], v[154:155], 0, s[18:19]
	s_mov_b32 s47, 0
	global_load_dwordx4 v[168:171], v[162:163], off
	s_mov_b32 s46, 0x2000
	v_lshl_add_u64 v[164:165], v[162:163], 0, s[46:47]
	global_load_dwordx4 v[172:175], v[164:165], off
	s_mov_b32 s46, 0x4000
	v_lshl_add_u64 v[164:165], v[162:163], 0, s[46:47]
	global_load_dwordx4 v[176:179], v[164:165], off
	s_mov_b32 s46, 0x6000
	v_lshl_add_u64 v[164:165], v[162:163], 0, s[46:47]
	global_load_dwordx4 v[180:183], v[164:165], off
	s_mov_b32 s46, 0x8000
	v_lshl_add_u64 v[164:165], v[162:163], 0, s[46:47]
	global_load_dwordx4 v[184:187], v[164:165], off
	s_mov_b32 s46, 0xa000
	v_lshl_add_u64 v[164:165], v[162:163], 0, s[46:47]
	global_load_dwordx4 v[204:207], v[164:165], off
	s_mov_b32 s46, 0xc000
	v_lshl_add_u64 v[164:165], v[162:163], 0, s[46:47]
	global_load_dwordx4 v[208:211], v[164:165], off
	s_mov_b32 s46, 0xe000
	v_lshl_add_u64 v[164:165], v[162:163], 0, s[46:47]
	global_load_dwordx4 v[212:215], v[164:165], off
	s_and_b64 vcc, exec, s[8:9]
	s_cbranch_vccz .Lg0_nobar
	s_barrier

; #define PG8_STAGE(bufoff, gbase, voff) do { _Pragma("unroll") for (int _i = 0; _i < 2; ++_i) \
;         __builtin_amdgcn_global_load_lds((const unsigned*)((const char*)(gbase) + (voff)[_i]), (PG8_LAS unsigned*)(lds + (bufoff) + ldsw + _i * 8192), 16, 0, 0); } while (0)
; #define PG8_LDA(dst, b, h) do { _Pragma("unroll") for (int m = 0; m < 4; ++m) _Pragma("unroll") for (int k = 0; k < 2; ++k) dst[m][k] = *(const PG8_LAS bf16x8*)(lds + PG8_SA(b, h) + aoff + m * 2048 + k * 1024); } while (0)
; #define PG8_LDB(dst, b, h) do { _Pragma("unroll") for (int n = 0; n < 2; ++n) _Pragma("unroll") for (int k = 0; k < 2; ++k) dst[n][k] = *(const PG8_LAS bf16x8*)(lds + PG8_SB(b, h) + boff + n * 2048 + k * 1024); } while (0)
; #define PG8_MMA(ai, bj, At, Bt) do { __builtin_amdgcn_s_setprio(1); _Pragma("unroll") for (int m = 0; m < 4; ++m) _Pragma("unroll") for (int n = 0; n < 2; ++n) _Pragma("unroll") for (int k = 0; k < 2; ++k) \
;         acc[ai][bj][m][n] = __builtin_amdgcn_mfma_f32_16x16x32_bf16(Bt[n][k], At[m][k], acc[ai][bj][m][n], 0, 0, 0); __builtin_amdgcn_s_setprio(0); } while (0)
; #define PG8_WAIT_V(n) asm volatile("s_waitcnt vmcnt(" #n ")" ::: "memory")
; #define PG8_WAIT_L(n) asm volatile("s_waitcnt lgkmcnt(" #n ")" ::: "memory")
; template <class Epi, class Sched, bool ALIGN_EPI = false, bool SP2 = false>
; __device__ __forceinline__ void gemm_phase(PG8_LAS unsigned char* lds, const Gemm g, const Sched& S, const Epi& E) {
;     ...
;             const bool last = (t == nt - 2);
;             const char* a1 = cA + (size_t)(t + 1) * kstep;
;             const char* a2 = last ? nA : cA + (size_t)(t + 2) * kstep; const char* b2 = last ? nB : cB + (size_t)(t + 2) * kstep;
;             const char* a3 = a2 + kstep; const char* b3 = b2 + kstep;
;             if (last && has_next) S.a_ready(nxt);
;             if constexpr (SP2) {
;             PG8_LDB(B0, 0, 0); PG8_LDB(B1, 0, 1); PG8_SCHED; PG8_LDA(At, 0, 0); PG8_STAGE(PG8_SA(1, 1), a1 + hstep, voffA);
;             PG8_WAIT_V(8); PG8_WAIT_L(0); PG8_BAR; PG8_MMA(0, 0, At, B0); PG8_MMA(0, 1, At, B1); PG8_BAR; PG8_SCHED;
;             PG8_LDA(At, 0, 1); PG8_STAGE(PG8_SB(0, 0), b2, voffB); PG8_STAGE(PG8_SB(0, 1), b2 + hstep, voffB); PG8_STAGE(PG8_SA(0, 0), a2, voffA);
;             PG8_WAIT_V(8); PG8_WAIT_L(0); PG8_BAR; PG8_MMA(1, 0, At, B0); PG8_MMA(1, 1, At, B1); PG8_BAR; PG8_SCHED;
.LBB0_160:
	s_add_u32 s42, s36, 0x100
	s_addc_u32 s43, s37, 0
	s_add_i32 s47, 0, 0x10000
	s_cmp_eq_u32 s46, 20
	s_cselect_b32 s45, s1, s43
	s_cselect_b32 s44, s0, s42
	s_cselect_b32 s19, s7, s73
	s_cselect_b32 s18, s6, s60
	s_add_i32 s76, 0, 0x14000
	v_add_u32_e32 v174, s47, v143
	v_add_u32_e32 v186, s76, v143
	ds_read_b128 v[160:163], v174
	ds_read_b128 v[164:167], v174 offset:1024
	ds_read_b128 v[170:173], v174 offset:2048
	ds_read_b128 v[174:177], v174 offset:3072
	ds_read_b128 v[178:181], v186
	ds_read_b128 v[182:185], v186 offset:1024
	ds_read_b128 v[204:207], v186 offset:2048
	ds_read_b128 v[208:211], v186 offset:3072
	v_lshl_add_u64 v[186:187], s[36:37], 0, v[156:157]
	s_add_i32 m0, s54, 0xc000
	ds_read_b128 v[212:215], v169
	ds_read_b128 v[216:219], v169 offset:1024
	ds_read_b128 v[220:223], v169 offset:2048
	ds_read_b128 v[224:227], v169 offset:3072
	ds_read_b128 v[228:231], v169 offset:4096
	ds_read_b128 v[232:235], v169 offset:5120
	ds_read_b128 v[236:239], v169 offset:6144
	ds_read_b128 v[240:243], v169 offset:7168
	global_load_lds_dwordx4 v[186:187], off
	v_lshl_add_u64 v[186:187], s[36:37], 0, v[158:159]
	s_add_i32 m0, s54, 0xe000
	s_nop 0
	global_load_lds_dwordx4 v[186:187], off
	s_waitcnt vmcnt(8)
	s_waitcnt lgkmcnt(0)
	s_setprio 1
	s_barrier
	v_mfma_f32_16x16x32_bf16 v[126:129], v[160:163], v[212:215], v[126:129]
	v_mfma_f32_16x16x32_bf16 v[122:125], v[170:173], v[212:215], v[122:125]
	v_mfma_f32_16x16x32_bf16 v[110:113], v[160:163], v[220:223], v[110:113]
	v_mfma_f32_16x16x32_bf16 v[106:109], v[170:173], v[220:223], v[106:109]
	v_mfma_f32_16x16x32_bf16 v[94:97], v[160:163], v[228:231], v[94:97]
	v_mfma_f32_16x16x32_bf16 v[90:93], v[170:173], v[228:231], v[90:93]
	v_mfma_f32_16x16x32_bf16 v[78:81], v[160:163], v[236:239], v[78:81]
	v_mfma_f32_16x16x32_bf16 v[74:77], v[170:173], v[236:239], v[74:77]
	s_setprio 0
	s_setprio 1
	v_mfma_f32_16x16x32_bf16 v[126:129], v[164:167], v[216:219], v[126:129]
	v_mfma_f32_16x16x32_bf16 v[122:125], v[174:177], v[216:219], v[122:125]
	v_mfma_f32_16x16x32_bf16 v[110:113], v[164:167], v[224:227], v[110:113]
	v_mfma_f32_16x16x32_bf16 v[106:109], v[174:177], v[224:227], v[106:109]
	v_mfma_f32_16x16x32_bf16 v[94:97], v[164:167], v[232:235], v[94:97]
	v_mfma_f32_16x16x32_bf16 v[90:93], v[174:177], v[232:235], v[90:93]
	v_mfma_f32_16x16x32_bf16 v[78:81], v[164:167], v[240:243], v[78:81]
	v_mfma_f32_16x16x32_bf16 v[74:77], v[174:177], v[240:243], v[74:77]
	s_setprio 0
	s_setprio 1
	v_mfma_f32_16x16x32_bf16 v[118:121], v[178:181], v[212:215], v[118:121]
	v_mfma_f32_16x16x32_bf16 v[114:117], v[204:207], v[212:215], v[114:117]
	v_mfma_f32_16x16x32_bf16 v[102:105], v[178:181], v[220:223], v[102:105]
	v_mfma_f32_16x16x32_bf16 v[98:101], v[204:207], v[220:223], v[98:101]
	v_mfma_f32_16x16x32_bf16 v[86:89], v[178:181], v[228:231], v[86:89]
	v_mfma_f32_16x16x32_bf16 v[82:85], v[204:207], v[228:231], v[82:85]
	v_mfma_f32_16x16x32_bf16 v[70:73], v[178:181], v[236:239], v[70:73]
	v_mfma_f32_16x16x32_bf16 v[66:69], v[204:207], v[236:239], v[66:69]
	s_setprio 0
	s_setprio 1
	v_mfma_f32_16x16x32_bf16 v[118:121], v[182:185], v[216:219], v[118:121]
	v_mfma_f32_16x16x32_bf16 v[114:117], v[208:211], v[216:219], v[114:117]
	v_mfma_f32_16x16x32_bf16 v[102:105], v[182:185], v[224:227], v[102:105]
	v_mfma_f32_16x16x32_bf16 v[98:101], v[208:211], v[224:227], v[98:101]
	v_mfma_f32_16x16x32_bf16 v[86:89], v[182:185], v[232:235], v[86:89]
	v_mfma_f32_16x16x32_bf16 v[82:85], v[208:211], v[232:235], v[82:85]
	v_mfma_f32_16x16x32_bf16 v[70:73], v[182:185], v[240:243], v[70:73]
	v_mfma_f32_16x16x32_bf16 v[66:69], v[208:211], v[240:243], v[66:69]
	s_setprio 0
	s_barrier
	s_add_i32 s36, s47, s4
	v_lshl_add_u64 v[186:187], s[18:19], 0, v[148:149]
	s_mov_b32 m0, s36
	ds_read_b128 v[212:215], v169 offset:16384
	ds_read_b128 v[216:219], v169 offset:17408
	ds_read_b128 v[220:223], v169 offset:18432
	ds_read_b128 v[224:227], v169 offset:19456
	ds_read_b128 v[228:231], v169 offset:20480
	ds_read_b128 v[232:235], v169 offset:21504
	ds_read_b128 v[236:239], v169 offset:22528
	ds_read_b128 v[240:243], v169 offset:23552
	global_load_lds_dwordx4 v[186:187], off
	s_add_i32 m0, s36, 0x2000
	s_add_u32 s36, s18, 0x60000
	v_lshl_add_u64 v[244:245], s[18:19], 0, v[144:145]
	s_addc_u32 s37, s19, 0
	s_add_i32 s47, s76, s4
	global_load_lds_dwordx4 v[244:245], off
	v_lshl_add_u64 v[246:247], s[36:37], 0, v[148:149]
	s_mov_b32 m0, s47
	v_lshl_add_u64 v[248:249], s[44:45], 0, v[146:147]
	global_load_lds_dwordx4 v[246:247], off
	v_lshl_add_u64 v[246:247], s[36:37], 0, v[144:145]
	s_add_i32 m0, s47, 0x2000
	s_nop 0
	global_load_lds_dwordx4 v[246:247], off
	v_lshl_add_u64 v[246:247], s[44:45], 0, v[150:151]
	s_mov_b32 m0, s54
	s_nop 0
	global_load_lds_dwordx4 v[246:247], off
	s_mov_b32 m0, s57
	s_nop 0
	global_load_lds_dwordx4 v[248:249], off
	s_waitcnt vmcnt(8)
	s_waitcnt lgkmcnt(0)
	s_setprio 1
	s_barrier
; #define PG8_STAGE(bufoff, gbase, voff) do { _Pragma("unroll") for (int _i = 0; _i < 2; ++_i) \
;         __builtin_amdgcn_global_load_lds((const unsigned*)((const char*)(gbase) + (voff)[_i]), (PG8_LAS unsigned*)(lds + (bufoff) + ldsw + _i * 8192), 16, 0, 0); } while (0)
; #define PG8_LDA(dst, b, h) do { _Pragma("unroll") for (int m = 0; m < 4; ++m) _Pragma("unroll") for (int k = 0; k < 2; ++k) dst[m][k] = *(const PG8_LAS bf16x8*)(lds + PG8_SA(b, h) + aoff + m * 2048 + k * 1024); } while (0)
; #define PG8_LDB(dst, b, h) do { _Pragma("unroll") for (int n = 0; n < 2; ++n) _Pragma("unroll") for (int k = 0; k < 2; ++k) dst[n][k] = *(const PG8_LAS bf16x8*)(lds + PG8_SB(b, h) + boff + n * 2048 + k * 1024); } while (0)
; #define PG8_MMA(ai, bj, At, Bt) do { __builtin_amdgcn_s_setprio(1); _Pragma("unroll") for (int m = 0; m < 4; ++m) _Pragma("unroll") for (int n = 0; n < 2; ++n) _Pragma("unroll") for (int k = 0; k < 2; ++k) \
;         acc[ai][bj][m][n] = __builtin_amdgcn_mfma_f32_16x16x32_bf16(Bt[n][k], At[m][k], acc[ai][bj][m][n], 0, 0, 0); __builtin_amdgcn_s_setprio(0); } while (0)
; #define PG8_WAIT_V(n) asm volatile("s_waitcnt vmcnt(" #n ")" ::: "memory")
; #define PG8_WAIT_L(n) asm volatile("s_waitcnt lgkmcnt(" #n ")" ::: "memory")
; #define PG8_BAR __builtin_amdgcn_s_barrier()
; #define PG8_SCHED __builtin_amdgcn_sched_barrier(0)
; template <class Epi, class Sched, bool ALIGN_EPI = false, bool SP2 = false>
; __device__ __forceinline__ void gemm_phase(PG8_LAS unsigned char* lds, const Gemm g, const Sched& S, const Epi& E) {
;     ...
;             PG8_WAIT_V(8); PG8_WAIT_L(0); PG8_BAR; PG8_MMA(1, 0, At, B0); PG8_MMA(1, 1, At, B1); PG8_BAR; PG8_SCHED;
;             PG8_LDB(B0, 1, 0); PG8_LDB(B1, 1, 1); PG8_SCHED; PG8_LDA(At, 1, 0); PG8_STAGE(PG8_SA(0, 1), a2 + hstep, voffA);
;             PG8_WAIT_V(8); PG8_WAIT_L(0); PG8_BAR; PG8_MMA(0, 0, At, B0); PG8_MMA(0, 1, At, B1); PG8_BAR; PG8_SCHED;
	v_mfma_f32_16x16x32_bf16 v[62:65], v[160:163], v[212:215], v[62:65]
	v_mfma_f32_16x16x32_bf16 v[58:61], v[170:173], v[212:215], v[58:61]
	v_mfma_f32_16x16x32_bf16 v[46:49], v[160:163], v[220:223], v[46:49]
	v_mfma_f32_16x16x32_bf16 v[42:45], v[170:173], v[220:223], v[42:45]
	v_mfma_f32_16x16x32_bf16 v[30:33], v[160:163], v[228:231], v[30:33]
	v_mfma_f32_16x16x32_bf16 v[26:29], v[170:173], v[228:231], v[26:29]
	v_mfma_f32_16x16x32_bf16 v[14:17], v[160:163], v[236:239], v[14:17]
	v_mfma_f32_16x16x32_bf16 v[10:13], v[170:173], v[236:239], v[10:13]
	v_mfma_f32_16x16x32_bf16 v[62:65], v[164:167], v[216:219], v[62:65]
	v_mfma_f32_16x16x32_bf16 v[58:61], v[174:177], v[216:219], v[58:61]
	v_mfma_f32_16x16x32_bf16 v[46:49], v[164:167], v[224:227], v[46:49]
	v_mfma_f32_16x16x32_bf16 v[42:45], v[174:177], v[224:227], v[42:45]
	v_mfma_f32_16x16x32_bf16 v[30:33], v[164:167], v[232:235], v[30:33]
	v_mfma_f32_16x16x32_bf16 v[26:29], v[174:177], v[232:235], v[26:29]
	v_mfma_f32_16x16x32_bf16 v[14:17], v[164:167], v[240:243], v[14:17]
	v_mfma_f32_16x16x32_bf16 v[10:13], v[174:177], v[240:243], v[10:13]
	v_mfma_f32_16x16x32_bf16 v[54:57], v[178:181], v[212:215], v[54:57]
	v_mfma_f32_16x16x32_bf16 v[50:53], v[204:207], v[212:215], v[50:53]
	v_mfma_f32_16x16x32_bf16 v[38:41], v[178:181], v[220:223], v[38:41]
	v_mfma_f32_16x16x32_bf16 v[34:37], v[204:207], v[220:223], v[34:37]
	v_mfma_f32_16x16x32_bf16 v[22:25], v[178:181], v[228:231], v[22:25]
	v_mfma_f32_16x16x32_bf16 v[18:21], v[204:207], v[228:231], v[18:21]
	v_mfma_f32_16x16x32_bf16 v[6:9], v[178:181], v[236:239], v[6:9]
	v_mfma_f32_16x16x32_bf16 v[2:5], v[204:207], v[236:239], v[2:5]
	v_mfma_f32_16x16x32_bf16 v[54:57], v[182:185], v[216:219], v[54:57]
	v_mfma_f32_16x16x32_bf16 v[50:53], v[208:211], v[216:219], v[50:53]
	v_mfma_f32_16x16x32_bf16 v[38:41], v[182:185], v[224:227], v[38:41]
	v_mfma_f32_16x16x32_bf16 v[34:37], v[208:211], v[224:227], v[34:37]
	v_mfma_f32_16x16x32_bf16 v[22:25], v[182:185], v[232:235], v[22:25]
	v_mfma_f32_16x16x32_bf16 v[18:21], v[208:211], v[232:235], v[18:21]
	v_mfma_f32_16x16x32_bf16 v[6:9], v[182:185], v[240:243], v[6:9]
	v_mfma_f32_16x16x32_bf16 v[2:5], v[208:211], v[240:243], v[2:5]
	s_setprio 0
	s_barrier
	s_add_i32 s47, 0, 0x18000
	s_add_i32 s76, 0, 0x1c000
	v_add_u32_e32 v174, s47, v143
	v_add_u32_e32 v203, s76, v143
	ds_read_b128 v[160:163], v174
	ds_read_b128 v[164:167], v174 offset:1024
	ds_read_b128 v[170:173], v174 offset:2048
	ds_read_b128 v[174:177], v174 offset:3072
	ds_read_b128 v[178:181], v203
	ds_read_b128 v[182:185], v203 offset:1024
	ds_read_b128 v[204:207], v203 offset:2048
	ds_read_b128 v[208:211], v203 offset:3072
	s_add_u32 s36, s44, 0x60000
	s_addc_u32 s37, s45, 0
	s_mov_b32 m0, s58
	v_lshl_add_u64 v[250:251], s[36:37], 0, v[150:151]
	ds_read_b128 v[212:215], v169 offset:32768
	ds_read_b128 v[216:219], v169 offset:33792
	ds_read_b128 v[220:223], v169 offset:34816
	ds_read_b128 v[224:227], v169 offset:35840
	ds_read_b128 v[228:231], v169 offset:36864
	ds_read_b128 v[232:235], v169 offset:37888
	ds_read_b128 v[236:239], v169 offset:38912
	ds_read_b128 v[240:243], v169 offset:39936
	global_load_lds_dwordx4 v[250:251], off
	v_lshl_add_u64 v[250:251], s[36:37], 0, v[146:147]
	s_mov_b32 m0, s59
	s_nop 0
	global_load_lds_dwordx4 v[250:251], off
	s_waitcnt vmcnt(8)
	s_waitcnt lgkmcnt(0)
	s_setprio 1
	s_barrier
	v_mfma_f32_16x16x32_bf16 v[126:129], v[160:163], v[212:215], v[126:129]
	v_mfma_f32_16x16x32_bf16 v[122:125], v[170:173], v[212:215], v[122:125]
	v_mfma_f32_16x16x32_bf16 v[110:113], v[160:163], v[220:223], v[110:113]
	v_mfma_f32_16x16x32_bf16 v[106:109], v[170:173], v[220:223], v[106:109]
	v_mfma_f32_16x16x32_bf16 v[94:97], v[160:163], v[228:231], v[94:97]
	v_mfma_f32_16x16x32_bf16 v[90:93], v[170:173], v[228:231], v[90:93]
	v_mfma_f32_16x16x32_bf16 v[78:81], v[160:163], v[236:239], v[78:81]
	v_mfma_f32_16x16x32_bf16 v[74:77], v[170:173], v[236:239], v[74:77]
	s_setprio 0
	s_setprio 1
	v_mfma_f32_16x16x32_bf16 v[126:129], v[164:167], v[216:219], v[126:129]
	v_mfma_f32_16x16x32_bf16 v[122:125], v[174:177], v[216:219], v[122:125]
	v_mfma_f32_16x16x32_bf16 v[110:113], v[164:167], v[224:227], v[110:113]
	v_mfma_f32_16x16x32_bf16 v[106:109], v[174:177], v[224:227], v[106:109]
	v_mfma_f32_16x16x32_bf16 v[94:97], v[164:167], v[232:235], v[94:97]
	v_mfma_f32_16x16x32_bf16 v[90:93], v[174:177], v[232:235], v[90:93]
	v_mfma_f32_16x16x32_bf16 v[78:81], v[164:167], v[240:243], v[78:81]
	v_mfma_f32_16x16x32_bf16 v[74:77], v[174:177], v[240:243], v[74:77]
	s_setprio 0
	s_setprio 1
	v_mfma_f32_16x16x32_bf16 v[118:121], v[178:181], v[212:215], v[118:121]
	v_mfma_f32_16x16x32_bf16 v[114:117], v[204:207], v[212:215], v[114:117]
	v_mfma_f32_16x16x32_bf16 v[102:105], v[178:181], v[220:223], v[102:105]
	v_mfma_f32_16x16x32_bf16 v[98:101], v[204:207], v[220:223], v[98:101]
	v_mfma_f32_16x16x32_bf16 v[86:89], v[178:181], v[228:231], v[86:89]
	v_mfma_f32_16x16x32_bf16 v[82:85], v[204:207], v[228:231], v[82:85]
	v_mfma_f32_16x16x32_bf16 v[70:73], v[178:181], v[236:239], v[70:73]
	v_mfma_f32_16x16x32_bf16 v[66:69], v[204:207], v[236:239], v[66:69]
	s_setprio 0
	s_setprio 1
	v_mfma_f32_16x16x32_bf16 v[118:121], v[182:185], v[216:219], v[118:121]
	v_mfma_f32_16x16x32_bf16 v[114:117], v[208:211], v[216:219], v[114:117]
	v_mfma_f32_16x16x32_bf16 v[102:105], v[182:185], v[224:227], v[102:105]
	v_mfma_f32_16x16x32_bf16 v[98:101], v[208:211], v[224:227], v[98:101]
	v_mfma_f32_16x16x32_bf16 v[86:89], v[182:185], v[232:235], v[86:89]
	v_mfma_f32_16x16x32_bf16 v[82:85], v[208:211], v[232:235], v[82:85]
	v_mfma_f32_16x16x32_bf16 v[70:73], v[182:185], v[240:243], v[70:73]
	v_mfma_f32_16x16x32_bf16 v[66:69], v[208:211], v[240:243], v[66:69]
	s_setprio 0
	s_barrier
; #define PG8_STAGE(bufoff, gbase, voff) do { _Pragma("unroll") for (int _i = 0; _i < 2; ++_i) \
;         __builtin_amdgcn_global_load_lds((const unsigned*)((const char*)(gbase) + (voff)[_i]), (PG8_LAS unsigned*)(lds + (bufoff) + ldsw + _i * 8192), 16, 0, 0); } while (0)
; #define PG8_LDA(dst, b, h) do { _Pragma("unroll") for (int m = 0; m < 4; ++m) _Pragma("unroll") for (int k = 0; k < 2; ++k) dst[m][k] = *(const PG8_LAS bf16x8*)(lds + PG8_SA(b, h) + aoff + m * 2048 + k * 1024); } while (0)
; #define PG8_MMA(ai, bj, At, Bt) do { __builtin_amdgcn_s_setprio(1); _Pragma("unroll") for (int m = 0; m < 4; ++m) _Pragma("unroll") for (int n = 0; n < 2; ++n) _Pragma("unroll") for (int k = 0; k < 2; ++k) \
;         acc[ai][bj][m][n] = __builtin_amdgcn_mfma_f32_16x16x32_bf16(Bt[n][k], At[m][k], acc[ai][bj][m][n], 0, 0, 0); __builtin_amdgcn_s_setprio(0); } while (0)
; #define PG8_WAIT_V(n) asm volatile("s_waitcnt vmcnt(" #n ")" ::: "memory")
; #define PG8_WAIT_L(n) asm volatile("s_waitcnt lgkmcnt(" #n ")" ::: "memory")
; #define PG8_BAR __builtin_amdgcn_s_barrier()
; #define PG8_SCHED __builtin_amdgcn_sched_barrier(0)
; template <class Epi, class Sched, bool ALIGN_EPI = false, bool SP2 = false>
; __device__ __forceinline__ void gemm_phase(PG8_LAS unsigned char* lds, const Gemm g, const Sched& S, const Epi& E) {
;     ...
;             PG8_LDA(At, 1, 1); PG8_STAGE(PG8_SB(1, 0), b3, voffB); PG8_STAGE(PG8_SB(1, 1), b3 + hstep, voffB); PG8_STAGE(PG8_SA(1, 0), a3, voffA);
;             PG8_WAIT_V(8); PG8_WAIT_L(0); PG8_BAR; PG8_MMA(1, 0, At, B0); PG8_MMA(1, 1, At, B1); PG8_BAR; PG8_SCHED;
;     ...
;         if constexpr (ALIGN_EPI) { if (wr == 0) PG8_BAR; }
	s_add_i32 s36, s47, s4
	v_lshl_add_u64 v[186:187], v[186:187], 0, s[68:69]
	s_mov_b32 m0, s36
	ds_read_b128 v[212:215], v169 offset:49152
	ds_read_b128 v[216:219], v169 offset:50176
	ds_read_b128 v[220:223], v169 offset:51200
	ds_read_b128 v[224:227], v169 offset:52224
	ds_read_b128 v[228:231], v169 offset:53248
	ds_read_b128 v[232:235], v169 offset:54272
	ds_read_b128 v[236:239], v169 offset:55296
	ds_read_b128 v[240:243], v169 offset:56320
	global_load_lds_dwordx4 v[186:187], off
	s_add_i32 m0, s36, 0x2000
	s_add_u32 s18, s18, 0x60080
	v_lshl_add_u64 v[186:187], v[244:245], 0, s[68:69]
	s_addc_u32 s19, s19, 0
	s_add_i32 s36, s76, s4
	global_load_lds_dwordx4 v[186:187], off
	v_lshl_add_u64 v[186:187], s[18:19], 0, v[148:149]
	s_mov_b32 m0, s36
	s_nop 0
	global_load_lds_dwordx4 v[186:187], off
	v_lshl_add_u64 v[186:187], s[18:19], 0, v[144:145]
	s_add_i32 m0, s36, 0x2000
	s_nop 0
	global_load_lds_dwordx4 v[186:187], off
	v_lshl_add_u64 v[186:187], v[246:247], 0, s[68:69]
	s_mov_b32 m0, s62
	s_nop 0
	global_load_lds_dwordx4 v[186:187], off
	v_lshl_add_u64 v[186:187], v[248:249], 0, s[68:69]
	s_mov_b32 m0, s63
	s_nop 0
	global_load_lds_dwordx4 v[186:187], off
	s_nop 0
	s_waitcnt vmcnt(8)
	s_waitcnt lgkmcnt(0)
	s_setprio 1
	s_barrier
	v_mfma_f32_16x16x32_bf16 v[62:65], v[160:163], v[212:215], v[62:65]
	v_mfma_f32_16x16x32_bf16 v[58:61], v[170:173], v[212:215], v[58:61]
	v_mfma_f32_16x16x32_bf16 v[46:49], v[160:163], v[220:223], v[46:49]
	v_mfma_f32_16x16x32_bf16 v[42:45], v[170:173], v[220:223], v[42:45]
	v_mfma_f32_16x16x32_bf16 v[30:33], v[160:163], v[228:231], v[30:33]
	v_mfma_f32_16x16x32_bf16 v[26:29], v[170:173], v[228:231], v[26:29]
	v_mfma_f32_16x16x32_bf16 v[14:17], v[160:163], v[236:239], v[14:17]
	v_mfma_f32_16x16x32_bf16 v[10:13], v[170:173], v[236:239], v[10:13]
	v_mfma_f32_16x16x32_bf16 v[62:65], v[164:167], v[216:219], v[62:65]
	v_mfma_f32_16x16x32_bf16 v[58:61], v[174:177], v[216:219], v[58:61]
	v_mfma_f32_16x16x32_bf16 v[46:49], v[164:167], v[224:227], v[46:49]
	v_mfma_f32_16x16x32_bf16 v[42:45], v[174:177], v[224:227], v[42:45]
	v_mfma_f32_16x16x32_bf16 v[30:33], v[164:167], v[232:235], v[30:33]
	v_mfma_f32_16x16x32_bf16 v[26:29], v[174:177], v[232:235], v[26:29]
	v_mfma_f32_16x16x32_bf16 v[14:17], v[164:167], v[240:243], v[14:17]
	v_mfma_f32_16x16x32_bf16 v[10:13], v[174:177], v[240:243], v[10:13]
	v_mfma_f32_16x16x32_bf16 v[54:57], v[178:181], v[212:215], v[54:57]
	v_mfma_f32_16x16x32_bf16 v[50:53], v[204:207], v[212:215], v[50:53]
	v_mfma_f32_16x16x32_bf16 v[38:41], v[178:181], v[220:223], v[38:41]
	v_mfma_f32_16x16x32_bf16 v[34:37], v[204:207], v[220:223], v[34:37]
	v_mfma_f32_16x16x32_bf16 v[22:25], v[178:181], v[228:231], v[22:25]
	v_mfma_f32_16x16x32_bf16 v[18:21], v[204:207], v[228:231], v[18:21]
	v_mfma_f32_16x16x32_bf16 v[6:9], v[178:181], v[236:239], v[6:9]
	v_mfma_f32_16x16x32_bf16 v[2:5], v[204:207], v[236:239], v[2:5]
	v_mfma_f32_16x16x32_bf16 v[54:57], v[182:185], v[216:219], v[54:57]
	v_mfma_f32_16x16x32_bf16 v[50:53], v[208:211], v[216:219], v[50:53]
	v_mfma_f32_16x16x32_bf16 v[38:41], v[182:185], v[224:227], v[38:41]
	v_mfma_f32_16x16x32_bf16 v[34:37], v[208:211], v[224:227], v[34:37]
	v_mfma_f32_16x16x32_bf16 v[22:25], v[182:185], v[232:235], v[22:25]
	v_mfma_f32_16x16x32_bf16 v[18:21], v[208:211], v[232:235], v[18:21]
	v_mfma_f32_16x16x32_bf16 v[6:9], v[182:185], v[240:243], v[6:9]
	v_mfma_f32_16x16x32_bf16 v[2:5], v[208:211], v[240:243], v[2:5]
	s_setprio 0
	s_barrier
	s_add_i32 s46, s46, 2
	s_add_u32 s60, s60, 0x100
	s_addc_u32 s73, s73, 0
	s_cmp_gt_u32 s46, 21
	s_mov_b64 s[36:37], s[42:43]
	s_cbranch_scc0 .LBB0_160
	s_and_b64 vcc, exec, s[10:11]
	s_cbranch_vccz .LBB0_163
	s_barrier

; #define PG8_STAGE(bufoff, gbase, voff) do { _Pragma("unroll") for (int _i = 0; _i < 2; ++_i) \
;         __builtin_amdgcn_global_load_lds((const unsigned*)((const char*)(gbase) + (voff)[_i]), (PG8_LAS unsigned*)(lds + (bufoff) + ldsw + _i * 8192), 16, 0, 0); } while (0)
; #define PG8_LDA(dst, b, h) do { _Pragma("unroll") for (int m = 0; m < 4; ++m) _Pragma("unroll") for (int k = 0; k < 2; ++k) dst[m][k] = *(const PG8_LAS bf16x8*)(lds + PG8_SA(b, h) + aoff + m * 2048 + k * 1024); } while (0)
; #define PG8_LDB(dst, b, h) do { _Pragma("unroll") for (int n = 0; n < 2; ++n) _Pragma("unroll") for (int k = 0; k < 2; ++k) dst[n][k] = *(const PG8_LAS bf16x8*)(lds + PG8_SB(b, h) + boff + n * 2048 + k * 1024); } while (0)
; #define PG8_MMA(ai, bj, At, Bt) do { __builtin_amdgcn_s_setprio(1); _Pragma("unroll") for (int m = 0; m < 4; ++m) _Pragma("unroll") for (int n = 0; n < 2; ++n) _Pragma("unroll") for (int k = 0; k < 2; ++k) \
;         acc[ai][bj][m][n] = __builtin_amdgcn_mfma_f32_16x16x32_bf16(Bt[n][k], At[m][k], acc[ai][bj][m][n], 0, 0, 0); __builtin_amdgcn_s_setprio(0); } while (0)
; #define PG8_WAIT_V(n) asm volatile("s_waitcnt vmcnt(" #n ")" ::: "memory")
; #define PG8_WAIT_L(n) asm volatile("s_waitcnt lgkmcnt(" #n ")" ::: "memory")
; #define PG8_BAR __builtin_amdgcn_s_barrier()
; #define PG8_SCHED __builtin_amdgcn_sched_barrier(0)
; template <class Epi, class Sched, bool ALIGN_EPI = false, bool SP2 = false>
; __device__ __forceinline__ void gemm_phase(PG8_LAS unsigned char* lds, const Gemm g, const Sched& S, const Epi& E) {
;     ...
;             const bool last = (t == nt - 2);
;             const char* a1 = cA + (size_t)(t + 1) * kstep;
;             const char* a2 = last ? nA : cA + (size_t)(t + 2) * kstep; const char* b2 = last ? nB : cB + (size_t)(t + 2) * kstep;
;             const char* a3 = a2 + kstep; const char* b3 = b2 + kstep;
;             if (last && has_next) S.a_ready(nxt);
;             if constexpr (SP2) {
;             PG8_LDB(B0, 0, 0); PG8_LDB(B1, 0, 1); PG8_SCHED; PG8_LDA(At, 0, 0); PG8_STAGE(PG8_SA(1, 1), a1 + hstep, voffA);
;             PG8_WAIT_V(8); PG8_WAIT_L(0); PG8_BAR; PG8_MMA(0, 0, At, B0); PG8_MMA(0, 1, At, B1); PG8_BAR; PG8_SCHED;
;             PG8_LDA(At, 0, 1); PG8_STAGE(PG8_SB(0, 0), b2, voffB); PG8_STAGE(PG8_SB(0, 1), b2 + hstep, voffB); PG8_STAGE(PG8_SA(0, 0), a2, voffA);
.LBB0_281:
	s_add_u32 s18, s36, 0xfff80080
	s_addc_u32 s19, s37, -1
	s_add_i32 s73, 0, 0x10000
	s_cmp_eq_u32 s67, 28
	s_cselect_b32 s43, s9, s19
	s_cselect_b32 s42, s59, s18
	v_add_u32_e32 v163, s73, v160
	s_cselect_b32 s19, s7, s63
	s_cselect_b32 s18, s60, s62
	s_add_i32 s76, 0, 0x14000
	ds_read_b128 v[156:159], v163
	ds_read_b128 v[164:167], v163 offset:1024
	ds_read_b128 v[168:171], v163 offset:2048
	ds_read_b128 v[172:175], v163 offset:3072
	v_add_u32_e32 v163, s76, v160
	ds_read_b128 v[176:179], v163
	ds_read_b128 v[180:183], v163 offset:1024
	ds_read_b128 v[184:187], v163 offset:2048
	ds_read_b128 v[204:207], v163 offset:3072
	v_lshl_add_u64 v[240:241], s[36:37], 0, v[152:153]
	s_add_i32 m0, s30, 0xc000
	ds_read_b128 v[208:211], v162
	ds_read_b128 v[212:215], v162 offset:1024
	ds_read_b128 v[216:219], v162 offset:2048
	ds_read_b128 v[220:223], v162 offset:3072
	ds_read_b128 v[224:227], v162 offset:4096
	ds_read_b128 v[228:231], v162 offset:5120
	ds_read_b128 v[232:235], v162 offset:6144
	ds_read_b128 v[236:239], v162 offset:7168
	global_load_lds_dwordx4 v[240:241], off
	v_lshl_add_u64 v[240:241], s[36:37], 0, v[154:155]
	s_add_i32 m0, s30, 0xe000
	s_nop 0
	global_load_lds_dwordx4 v[240:241], off
	s_nop 0
	s_nop 0
	s_waitcnt vmcnt(8)
	s_waitcnt lgkmcnt(0)
	s_setprio 1
	s_barrier
	v_mfma_f32_16x16x32_bf16 v[126:129], v[156:159], v[208:211], v[126:129]
	v_mfma_f32_16x16x32_bf16 v[122:125], v[168:171], v[208:211], v[122:125]
	v_mfma_f32_16x16x32_bf16 v[110:113], v[156:159], v[216:219], v[110:113]
	v_mfma_f32_16x16x32_bf16 v[106:109], v[168:171], v[216:219], v[106:109]
	v_mfma_f32_16x16x32_bf16 v[94:97], v[156:159], v[224:227], v[94:97]
	v_mfma_f32_16x16x32_bf16 v[90:93], v[168:171], v[224:227], v[90:93]
	v_mfma_f32_16x16x32_bf16 v[78:81], v[156:159], v[232:235], v[78:81]
	v_mfma_f32_16x16x32_bf16 v[74:77], v[168:171], v[232:235], v[74:77]
	s_setprio 0
	s_setprio 1
	v_mfma_f32_16x16x32_bf16 v[126:129], v[164:167], v[212:215], v[126:129]
	v_mfma_f32_16x16x32_bf16 v[122:125], v[172:175], v[212:215], v[122:125]
	v_mfma_f32_16x16x32_bf16 v[110:113], v[164:167], v[220:223], v[110:113]
	v_mfma_f32_16x16x32_bf16 v[106:109], v[172:175], v[220:223], v[106:109]
	v_mfma_f32_16x16x32_bf16 v[94:97], v[164:167], v[228:231], v[94:97]
	v_mfma_f32_16x16x32_bf16 v[90:93], v[172:175], v[228:231], v[90:93]
	v_mfma_f32_16x16x32_bf16 v[78:81], v[164:167], v[236:239], v[78:81]
	v_mfma_f32_16x16x32_bf16 v[74:77], v[172:175], v[236:239], v[74:77]
	s_setprio 0
	s_setprio 1
	v_mfma_f32_16x16x32_bf16 v[118:121], v[176:179], v[208:211], v[118:121]
	v_mfma_f32_16x16x32_bf16 v[114:117], v[184:187], v[208:211], v[114:117]
	v_mfma_f32_16x16x32_bf16 v[102:105], v[176:179], v[216:219], v[102:105]
	v_mfma_f32_16x16x32_bf16 v[98:101], v[184:187], v[216:219], v[98:101]
	v_mfma_f32_16x16x32_bf16 v[86:89], v[176:179], v[224:227], v[86:89]
	v_mfma_f32_16x16x32_bf16 v[82:85], v[184:187], v[224:227], v[82:85]
	v_mfma_f32_16x16x32_bf16 v[70:73], v[176:179], v[232:235], v[70:73]
	v_mfma_f32_16x16x32_bf16 v[66:69], v[184:187], v[232:235], v[66:69]
	s_setprio 0
	s_setprio 1
	v_mfma_f32_16x16x32_bf16 v[118:121], v[180:183], v[212:215], v[118:121]
	v_mfma_f32_16x16x32_bf16 v[114:117], v[204:207], v[212:215], v[114:117]
	v_mfma_f32_16x16x32_bf16 v[102:105], v[180:183], v[220:223], v[102:105]
	v_mfma_f32_16x16x32_bf16 v[98:101], v[204:207], v[220:223], v[98:101]
	v_mfma_f32_16x16x32_bf16 v[86:89], v[180:183], v[228:231], v[86:89]
	v_mfma_f32_16x16x32_bf16 v[82:85], v[204:207], v[228:231], v[82:85]
	v_mfma_f32_16x16x32_bf16 v[70:73], v[180:183], v[236:239], v[70:73]
	v_mfma_f32_16x16x32_bf16 v[66:69], v[204:207], v[236:239], v[66:69]
	s_setprio 0
	s_barrier
	s_add_i32 s73, s73, s28
	v_lshl_add_u64 v[240:241], s[18:19], 0, v[146:147]
	s_mov_b32 m0, s73
	ds_read_b128 v[208:211], v162 offset:16384
	ds_read_b128 v[212:215], v162 offset:17408
	ds_read_b128 v[216:219], v162 offset:18432
	ds_read_b128 v[220:223], v162 offset:19456
	ds_read_b128 v[224:227], v162 offset:20480
	ds_read_b128 v[228:231], v162 offset:21504
	ds_read_b128 v[232:235], v162 offset:22528
	ds_read_b128 v[236:239], v162 offset:23552
	global_load_lds_dwordx4 v[240:241], off
	s_add_i32 m0, s73, 0x2000
	s_add_u32 s78, s18, 0x80000
	v_lshl_add_u64 v[242:243], s[18:19], 0, v[142:143]
	s_addc_u32 s79, s19, 0
	s_add_i32 s73, s76, s28
	global_load_lds_dwordx4 v[242:243], off
	v_lshl_add_u64 v[244:245], s[78:79], 0, v[146:147]
	s_mov_b32 m0, s73
	v_lshl_add_u64 v[246:247], s[42:43], 0, v[144:145]
	global_load_lds_dwordx4 v[244:245], off
	v_lshl_add_u64 v[244:245], s[78:79], 0, v[142:143]
	s_add_i32 m0, s73, 0x2000
	s_nop 0
	global_load_lds_dwordx4 v[244:245], off
	v_lshl_add_u64 v[244:245], s[42:43], 0, v[148:149]
	s_mov_b32 m0, s30
	s_nop 0
	global_load_lds_dwordx4 v[244:245], off
	s_mov_b32 m0, s34
	s_nop 0
	global_load_lds_dwordx4 v[246:247], off
	s_waitcnt vmcnt(8)
	s_waitcnt lgkmcnt(0)
	s_setprio 1
	s_barrier
; #define PG8_STAGE(bufoff, gbase, voff) do { _Pragma("unroll") for (int _i = 0; _i < 2; ++_i) \
;         __builtin_amdgcn_global_load_lds((const unsigned*)((const char*)(gbase) + (voff)[_i]), (PG8_LAS unsigned*)(lds + (bufoff) + ldsw + _i * 8192), 16, 0, 0); } while (0)
; #define PG8_LDA(dst, b, h) do { _Pragma("unroll") for (int m = 0; m < 4; ++m) _Pragma("unroll") for (int k = 0; k < 2; ++k) dst[m][k] = *(const PG8_LAS bf16x8*)(lds + PG8_SA(b, h) + aoff + m * 2048 + k * 1024); } while (0)
; #define PG8_LDB(dst, b, h) do { _Pragma("unroll") for (int n = 0; n < 2; ++n) _Pragma("unroll") for (int k = 0; k < 2; ++k) dst[n][k] = *(const PG8_LAS bf16x8*)(lds + PG8_SB(b, h) + boff + n * 2048 + k * 1024); } while (0)
; #define PG8_MMA(ai, bj, At, Bt) do { __builtin_amdgcn_s_setprio(1); _Pragma("unroll") for (int m = 0; m < 4; ++m) _Pragma("unroll") for (int n = 0; n < 2; ++n) _Pragma("unroll") for (int k = 0; k < 2; ++k) \
;         acc[ai][bj][m][n] = __builtin_amdgcn_mfma_f32_16x16x32_bf16(Bt[n][k], At[m][k], acc[ai][bj][m][n], 0, 0, 0); __builtin_amdgcn_s_setprio(0); } while (0)
; #define PG8_WAIT_V(n) asm volatile("s_waitcnt vmcnt(" #n ")" ::: "memory")
; #define PG8_WAIT_L(n) asm volatile("s_waitcnt lgkmcnt(" #n ")" ::: "memory")
; #define PG8_BAR __builtin_amdgcn_s_barrier()
; #define PG8_SCHED __builtin_amdgcn_sched_barrier(0)
; template <class Epi, class Sched, bool ALIGN_EPI = false, bool SP2 = false>
; __device__ __forceinline__ void gemm_phase(PG8_LAS unsigned char* lds, const Gemm g, const Sched& S, const Epi& E) {
;     ...
;             PG8_WAIT_V(8); PG8_WAIT_L(0); PG8_BAR; PG8_MMA(1, 0, At, B0); PG8_MMA(1, 1, At, B1); PG8_BAR; PG8_SCHED;
;             PG8_LDB(B0, 1, 0); PG8_LDB(B1, 1, 1); PG8_SCHED; PG8_LDA(At, 1, 0); PG8_STAGE(PG8_SA(0, 1), a2 + hstep, voffA);
;             PG8_WAIT_V(8); PG8_WAIT_L(0); PG8_BAR; PG8_MMA(0, 0, At, B0); PG8_MMA(0, 1, At, B1); PG8_BAR; PG8_SCHED;
	v_mfma_f32_16x16x32_bf16 v[62:65], v[156:159], v[208:211], v[62:65]
	v_mfma_f32_16x16x32_bf16 v[58:61], v[168:171], v[208:211], v[58:61]
	v_mfma_f32_16x16x32_bf16 v[46:49], v[156:159], v[216:219], v[46:49]
	v_mfma_f32_16x16x32_bf16 v[42:45], v[168:171], v[216:219], v[42:45]
	v_mfma_f32_16x16x32_bf16 v[30:33], v[156:159], v[224:227], v[30:33]
	v_mfma_f32_16x16x32_bf16 v[26:29], v[168:171], v[224:227], v[26:29]
	v_mfma_f32_16x16x32_bf16 v[14:17], v[156:159], v[232:235], v[14:17]
	v_mfma_f32_16x16x32_bf16 v[10:13], v[168:171], v[232:235], v[10:13]
	v_mfma_f32_16x16x32_bf16 v[62:65], v[164:167], v[212:215], v[62:65]
	v_mfma_f32_16x16x32_bf16 v[58:61], v[172:175], v[212:215], v[58:61]
	v_mfma_f32_16x16x32_bf16 v[46:49], v[164:167], v[220:223], v[46:49]
	v_mfma_f32_16x16x32_bf16 v[42:45], v[172:175], v[220:223], v[42:45]
	v_mfma_f32_16x16x32_bf16 v[30:33], v[164:167], v[228:231], v[30:33]
	v_mfma_f32_16x16x32_bf16 v[26:29], v[172:175], v[228:231], v[26:29]
	v_mfma_f32_16x16x32_bf16 v[14:17], v[164:167], v[236:239], v[14:17]
	v_mfma_f32_16x16x32_bf16 v[10:13], v[172:175], v[236:239], v[10:13]
	v_mfma_f32_16x16x32_bf16 v[54:57], v[176:179], v[208:211], v[54:57]
	v_mfma_f32_16x16x32_bf16 v[50:53], v[184:187], v[208:211], v[50:53]
	v_mfma_f32_16x16x32_bf16 v[38:41], v[176:179], v[216:219], v[38:41]
	v_mfma_f32_16x16x32_bf16 v[34:37], v[184:187], v[216:219], v[34:37]
	v_mfma_f32_16x16x32_bf16 v[22:25], v[176:179], v[224:227], v[22:25]
	v_mfma_f32_16x16x32_bf16 v[18:21], v[184:187], v[224:227], v[18:21]
	v_mfma_f32_16x16x32_bf16 v[6:9], v[176:179], v[232:235], v[6:9]
	v_mfma_f32_16x16x32_bf16 v[2:5], v[184:187], v[232:235], v[2:5]
	v_mfma_f32_16x16x32_bf16 v[54:57], v[180:183], v[212:215], v[54:57]
	v_mfma_f32_16x16x32_bf16 v[50:53], v[204:207], v[212:215], v[50:53]
	v_mfma_f32_16x16x32_bf16 v[38:41], v[180:183], v[220:223], v[38:41]
	v_mfma_f32_16x16x32_bf16 v[34:37], v[204:207], v[220:223], v[34:37]
	v_mfma_f32_16x16x32_bf16 v[22:25], v[180:183], v[228:231], v[22:25]
	v_mfma_f32_16x16x32_bf16 v[18:21], v[204:207], v[228:231], v[18:21]
	v_mfma_f32_16x16x32_bf16 v[6:9], v[180:183], v[236:239], v[6:9]
	v_mfma_f32_16x16x32_bf16 v[2:5], v[204:207], v[236:239], v[2:5]
	s_setprio 0
	s_barrier
	s_add_i32 s73, 0, 0x18000
	v_add_u32_e32 v163, s73, v160
	s_add_i32 s76, 0, 0x1c000
	ds_read_b128 v[156:159], v163
	ds_read_b128 v[164:167], v163 offset:1024
	ds_read_b128 v[168:171], v163 offset:2048
	ds_read_b128 v[172:175], v163 offset:3072
	v_add_u32_e32 v163, s76, v160
	ds_read_b128 v[176:179], v163
	ds_read_b128 v[180:183], v163 offset:1024
	ds_read_b128 v[184:187], v163 offset:2048
	ds_read_b128 v[204:207], v163 offset:3072
	s_add_u32 s42, s42, 0x80000
	s_addc_u32 s43, s43, 0
	s_mov_b32 m0, s44
	v_lshl_add_u64 v[248:249], s[42:43], 0, v[148:149]
	ds_read_b128 v[208:211], v162 offset:32768
	ds_read_b128 v[212:215], v162 offset:33792
	ds_read_b128 v[216:219], v162 offset:34816
	ds_read_b128 v[220:223], v162 offset:35840
	ds_read_b128 v[224:227], v162 offset:36864
	ds_read_b128 v[228:231], v162 offset:37888
	ds_read_b128 v[232:235], v162 offset:38912
	ds_read_b128 v[236:239], v162 offset:39936
	global_load_lds_dwordx4 v[248:249], off
	v_lshl_add_u64 v[248:249], s[42:43], 0, v[144:145]
	s_mov_b32 m0, s45
	s_nop 0
	global_load_lds_dwordx4 v[248:249], off
	s_waitcnt vmcnt(8)
	s_waitcnt lgkmcnt(0)
	s_setprio 1
	s_barrier
	v_mfma_f32_16x16x32_bf16 v[126:129], v[156:159], v[208:211], v[126:129]
	v_mfma_f32_16x16x32_bf16 v[122:125], v[168:171], v[208:211], v[122:125]
	v_mfma_f32_16x16x32_bf16 v[110:113], v[156:159], v[216:219], v[110:113]
	v_mfma_f32_16x16x32_bf16 v[106:109], v[168:171], v[216:219], v[106:109]
	v_mfma_f32_16x16x32_bf16 v[94:97], v[156:159], v[224:227], v[94:97]
	v_mfma_f32_16x16x32_bf16 v[90:93], v[168:171], v[224:227], v[90:93]
	v_mfma_f32_16x16x32_bf16 v[78:81], v[156:159], v[232:235], v[78:81]
	v_mfma_f32_16x16x32_bf16 v[74:77], v[168:171], v[232:235], v[74:77]
	s_setprio 0
	s_setprio 1
	v_mfma_f32_16x16x32_bf16 v[126:129], v[164:167], v[212:215], v[126:129]
	v_mfma_f32_16x16x32_bf16 v[122:125], v[172:175], v[212:215], v[122:125]
	v_mfma_f32_16x16x32_bf16 v[110:113], v[164:167], v[220:223], v[110:113]
	v_mfma_f32_16x16x32_bf16 v[106:109], v[172:175], v[220:223], v[106:109]
	v_mfma_f32_16x16x32_bf16 v[94:97], v[164:167], v[228:231], v[94:97]
	v_mfma_f32_16x16x32_bf16 v[90:93], v[172:175], v[228:231], v[90:93]
	v_mfma_f32_16x16x32_bf16 v[78:81], v[164:167], v[236:239], v[78:81]
	v_mfma_f32_16x16x32_bf16 v[74:77], v[172:175], v[236:239], v[74:77]
	s_setprio 0
	s_setprio 1
	v_mfma_f32_16x16x32_bf16 v[118:121], v[176:179], v[208:211], v[118:121]
	v_mfma_f32_16x16x32_bf16 v[114:117], v[184:187], v[208:211], v[114:117]
	v_mfma_f32_16x16x32_bf16 v[102:105], v[176:179], v[216:219], v[102:105]
	v_mfma_f32_16x16x32_bf16 v[98:101], v[184:187], v[216:219], v[98:101]
	v_mfma_f32_16x16x32_bf16 v[86:89], v[176:179], v[224:227], v[86:89]
	v_mfma_f32_16x16x32_bf16 v[82:85], v[184:187], v[224:227], v[82:85]
	v_mfma_f32_16x16x32_bf16 v[70:73], v[176:179], v[232:235], v[70:73]
	v_mfma_f32_16x16x32_bf16 v[66:69], v[184:187], v[232:235], v[66:69]
	s_setprio 0
	s_setprio 1
	v_mfma_f32_16x16x32_bf16 v[118:121], v[180:183], v[212:215], v[118:121]
	v_mfma_f32_16x16x32_bf16 v[114:117], v[204:207], v[212:215], v[114:117]
	v_mfma_f32_16x16x32_bf16 v[102:105], v[180:183], v[220:223], v[102:105]
	v_mfma_f32_16x16x32_bf16 v[98:101], v[204:207], v[220:223], v[98:101]
	v_mfma_f32_16x16x32_bf16 v[86:89], v[180:183], v[228:231], v[86:89]
	v_mfma_f32_16x16x32_bf16 v[82:85], v[204:207], v[228:231], v[82:85]
	v_mfma_f32_16x16x32_bf16 v[70:73], v[180:183], v[236:239], v[70:73]
	v_mfma_f32_16x16x32_bf16 v[66:69], v[204:207], v[236:239], v[66:69]
	s_setprio 0
	s_barrier
; #define PG8_STAGE(bufoff, gbase, voff) do { _Pragma("unroll") for (int _i = 0; _i < 2; ++_i) \
;         __builtin_amdgcn_global_load_lds((const unsigned*)((const char*)(gbase) + (voff)[_i]), (PG8_LAS unsigned*)(lds + (bufoff) + ldsw + _i * 8192), 16, 0, 0); } while (0)
; #define PG8_LDA(dst, b, h) do { _Pragma("unroll") for (int m = 0; m < 4; ++m) _Pragma("unroll") for (int k = 0; k < 2; ++k) dst[m][k] = *(const PG8_LAS bf16x8*)(lds + PG8_SA(b, h) + aoff + m * 2048 + k * 1024); } while (0)
; #define PG8_MMA(ai, bj, At, Bt) do { __builtin_amdgcn_s_setprio(1); _Pragma("unroll") for (int m = 0; m < 4; ++m) _Pragma("unroll") for (int n = 0; n < 2; ++n) _Pragma("unroll") for (int k = 0; k < 2; ++k) \
;         acc[ai][bj][m][n] = __builtin_amdgcn_mfma_f32_16x16x32_bf16(Bt[n][k], At[m][k], acc[ai][bj][m][n], 0, 0, 0); __builtin_amdgcn_s_setprio(0); } while (0)
; #define PG8_WAIT_V(n) asm volatile("s_waitcnt vmcnt(" #n ")" ::: "memory")
; #define PG8_WAIT_L(n) asm volatile("s_waitcnt lgkmcnt(" #n ")" ::: "memory")
; #define PG8_BAR __builtin_amdgcn_s_barrier()
; #define PG8_SCHED __builtin_amdgcn_sched_barrier(0)
; template <class Epi, class Sched, bool ALIGN_EPI = false, bool SP2 = false>
; __device__ __forceinline__ void gemm_phase(PG8_LAS unsigned char* lds, const Gemm g, const Sched& S, const Epi& E) {
;     ...
;             PG8_LDA(At, 1, 1); PG8_STAGE(PG8_SB(1, 0), b3, voffB); PG8_STAGE(PG8_SB(1, 1), b3 + hstep, voffB); PG8_STAGE(PG8_SA(1, 0), a3, voffA);
;             PG8_WAIT_V(8); PG8_WAIT_L(0); PG8_BAR; PG8_MMA(1, 0, At, B0); PG8_MMA(1, 1, At, B1); PG8_BAR; PG8_SCHED;
	s_add_i32 s42, s73, s28
	v_lshl_add_u64 v[240:241], v[240:241], 0, s[68:69]
	s_mov_b32 m0, s42
	ds_read_b128 v[208:211], v162 offset:49152
	ds_read_b128 v[212:215], v162 offset:50176
	ds_read_b128 v[216:219], v162 offset:51200
	ds_read_b128 v[220:223], v162 offset:52224
	ds_read_b128 v[224:227], v162 offset:53248
	ds_read_b128 v[228:231], v162 offset:54272
	ds_read_b128 v[232:235], v162 offset:55296
	ds_read_b128 v[236:239], v162 offset:56320
	global_load_lds_dwordx4 v[240:241], off
	s_add_i32 m0, s42, 0x2000
	s_add_u32 s18, s18, 0x80080
	v_lshl_add_u64 v[240:241], v[242:243], 0, s[68:69]
	s_addc_u32 s19, s19, 0
	s_add_i32 s42, s76, s28
	global_load_lds_dwordx4 v[240:241], off
	v_lshl_add_u64 v[240:241], s[18:19], 0, v[146:147]
	s_mov_b32 m0, s42
	s_nop 0
	global_load_lds_dwordx4 v[240:241], off
	v_lshl_add_u64 v[240:241], s[18:19], 0, v[142:143]
	s_add_i32 m0, s42, 0x2000
	s_nop 0
	global_load_lds_dwordx4 v[240:241], off
	v_lshl_add_u64 v[240:241], v[244:245], 0, s[68:69]
	s_mov_b32 m0, s46
	s_nop 0
	global_load_lds_dwordx4 v[240:241], off
	v_lshl_add_u64 v[240:241], v[246:247], 0, s[68:69]
	s_mov_b32 m0, s47
	s_nop 0
	global_load_lds_dwordx4 v[240:241], off
	s_nop 0
	s_waitcnt vmcnt(8)
	s_waitcnt lgkmcnt(0)
	s_setprio 1
	s_barrier
	v_mfma_f32_16x16x32_bf16 v[62:65], v[156:159], v[208:211], v[62:65]
	v_mfma_f32_16x16x32_bf16 v[58:61], v[168:171], v[208:211], v[58:61]
	v_mfma_f32_16x16x32_bf16 v[46:49], v[156:159], v[216:219], v[46:49]
	v_mfma_f32_16x16x32_bf16 v[42:45], v[168:171], v[216:219], v[42:45]
	v_mfma_f32_16x16x32_bf16 v[30:33], v[156:159], v[224:227], v[30:33]
	v_mfma_f32_16x16x32_bf16 v[26:29], v[168:171], v[224:227], v[26:29]
	v_mfma_f32_16x16x32_bf16 v[14:17], v[156:159], v[232:235], v[14:17]
	v_mfma_f32_16x16x32_bf16 v[10:13], v[168:171], v[232:235], v[10:13]
	v_mfma_f32_16x16x32_bf16 v[62:65], v[164:167], v[212:215], v[62:65]
	v_mfma_f32_16x16x32_bf16 v[58:61], v[172:175], v[212:215], v[58:61]
	v_mfma_f32_16x16x32_bf16 v[46:49], v[164:167], v[220:223], v[46:49]
	v_mfma_f32_16x16x32_bf16 v[42:45], v[172:175], v[220:223], v[42:45]
	v_mfma_f32_16x16x32_bf16 v[30:33], v[164:167], v[228:231], v[30:33]
	v_mfma_f32_16x16x32_bf16 v[26:29], v[172:175], v[228:231], v[26:29]
	v_mfma_f32_16x16x32_bf16 v[14:17], v[164:167], v[236:239], v[14:17]
	v_mfma_f32_16x16x32_bf16 v[10:13], v[172:175], v[236:239], v[10:13]
	v_mfma_f32_16x16x32_bf16 v[54:57], v[176:179], v[208:211], v[54:57]
	v_mfma_f32_16x16x32_bf16 v[50:53], v[184:187], v[208:211], v[50:53]
	v_mfma_f32_16x16x32_bf16 v[38:41], v[176:179], v[216:219], v[38:41]
	v_mfma_f32_16x16x32_bf16 v[34:37], v[184:187], v[216:219], v[34:37]
	v_mfma_f32_16x16x32_bf16 v[22:25], v[176:179], v[224:227], v[22:25]
	v_mfma_f32_16x16x32_bf16 v[18:21], v[184:187], v[224:227], v[18:21]
	v_mfma_f32_16x16x32_bf16 v[6:9], v[176:179], v[232:235], v[6:9]
	v_mfma_f32_16x16x32_bf16 v[2:5], v[184:187], v[232:235], v[2:5]
	v_mfma_f32_16x16x32_bf16 v[54:57], v[180:183], v[212:215], v[54:57]
	v_mfma_f32_16x16x32_bf16 v[50:53], v[204:207], v[212:215], v[50:53]
	v_mfma_f32_16x16x32_bf16 v[38:41], v[180:183], v[220:223], v[38:41]
	v_mfma_f32_16x16x32_bf16 v[34:37], v[204:207], v[220:223], v[34:37]
	v_mfma_f32_16x16x32_bf16 v[22:25], v[180:183], v[228:231], v[22:25]
	v_mfma_f32_16x16x32_bf16 v[18:21], v[204:207], v[228:231], v[18:21]
	v_mfma_f32_16x16x32_bf16 v[6:9], v[180:183], v[236:239], v[6:9]
	v_mfma_f32_16x16x32_bf16 v[2:5], v[204:207], v[236:239], v[2:5]
	s_setprio 0
	s_barrier
	s_add_i32 s67, s67, 2
	s_add_u32 s36, s36, 0x100
	s_addc_u32 s37, s37, 0
	s_add_u32 s62, s62, 0x100
	s_addc_u32 s63, s63, 0
	s_cmp_gt_u32 s67, 29
	s_cbranch_scc0 .LBB0_281
	s_and_b64 vcc, exec, s[4:5]
	s_cbranch_vccnz .LBB0_286
	s_cmp_lt_i32 s57, 30
	s_mov_b64 s[18:19], -1
	s_cbranch_scc1 .LBB0_287
